# all s_setprio removed from GEMM phases on top of the P4 rebalance + hand-written pooling/conversion
# speedup vs baseline: 1.0198x; 1.0003x over previous
.LBB0_199:
	ds_read_b128 v[104:107], v213
	ds_read_b128 v[108:111], v213 offset:1024
	ds_read_b128 v[136:139], v213 offset:2048
	ds_read_b128 v[140:143], v213 offset:3072
	ds_read_b128 v[144:147], v215
	ds_read_b128 v[162:165], v215 offset:1024
	ds_read_b128 v[166:169], v215 offset:2048
	ds_read_b128 v[170:173], v215 offset:3072
	s_add_u32 s0, s62, 0xfff80080
	s_addc_u32 s1, s63, -1
	s_cmp_eq_u32 s97, 28
	s_cselect_b32 s67, s7, s1
	s_cselect_b32 s66, s51, s0
	s_cselect_b32 s65, s53, s96
	s_cselect_b32 s64, s57, s95
	v_lshl_add_u64 v[206:207], s[62:63], 0, v[154:155]
	s_add_i32 m0, s69, 0xc000
	ds_read_b128 v[174:177], v216
	ds_read_b128 v[178:181], v216 offset:1024
	ds_read_b128 v[182:185], v216 offset:2048
	ds_read_b128 v[186:189], v216 offset:3072
	ds_read_b128 v[190:193], v216 offset:4096
	ds_read_b128 v[194:197], v216 offset:5120
	ds_read_b128 v[198:201], v216 offset:6144
	ds_read_b128 v[202:205], v216 offset:7168
	global_load_lds_dwordx4 v[206:207], off
	v_lshl_add_u64 v[206:207], s[62:63], 0, v[156:157]
	s_add_i32 m0, s69, 0xe000
	s_nop 0
	global_load_lds_dwordx4 v[206:207], off
	s_waitcnt vmcnt(8)
	s_waitcnt lgkmcnt(0)
	s_barrier
	s_waitcnt lgkmcnt(0)
	v_mfma_f32_16x16x32_bf16 v[132:135], v[104:107], v[174:177], v[132:135]
	v_mfma_f32_16x16x32_bf16 v[128:131], v[136:139], v[174:177], v[128:131]
	v_mfma_f32_16x16x32_bf16 v[116:119], v[104:107], v[182:185], v[116:119]
	v_mfma_f32_16x16x32_bf16 v[112:115], v[136:139], v[182:185], v[112:115]
	v_mfma_f32_16x16x32_bf16 v[92:95], v[104:107], v[190:193], v[92:95]
	v_mfma_f32_16x16x32_bf16 v[88:91], v[136:139], v[190:193], v[88:91]
	v_mfma_f32_16x16x32_bf16 v[76:79], v[104:107], v[198:201], v[76:79]
	v_mfma_f32_16x16x32_bf16 v[72:75], v[136:139], v[198:201], v[72:75]
	v_mfma_f32_16x16x32_bf16 v[132:135], v[108:111], v[178:181], v[132:135]
	v_mfma_f32_16x16x32_bf16 v[128:131], v[140:143], v[178:181], v[128:131]
	v_mfma_f32_16x16x32_bf16 v[116:119], v[108:111], v[186:189], v[116:119]
	v_mfma_f32_16x16x32_bf16 v[112:115], v[140:143], v[186:189], v[112:115]
	v_mfma_f32_16x16x32_bf16 v[92:95], v[108:111], v[194:197], v[92:95]
	v_mfma_f32_16x16x32_bf16 v[88:91], v[140:143], v[194:197], v[88:91]
	v_mfma_f32_16x16x32_bf16 v[76:79], v[108:111], v[202:205], v[76:79]
	v_mfma_f32_16x16x32_bf16 v[72:75], v[140:143], v[202:205], v[72:75]
	v_mfma_f32_16x16x32_bf16 v[124:127], v[144:147], v[174:177], v[124:127]
	v_mfma_f32_16x16x32_bf16 v[120:123], v[166:169], v[174:177], v[120:123]
	v_mfma_f32_16x16x32_bf16 v[100:103], v[144:147], v[182:185], v[100:103]
	v_mfma_f32_16x16x32_bf16 v[96:99], v[166:169], v[182:185], v[96:99]
	v_mfma_f32_16x16x32_bf16 v[84:87], v[144:147], v[190:193], v[84:87]
	v_mfma_f32_16x16x32_bf16 v[80:83], v[166:169], v[190:193], v[80:83]
	v_mfma_f32_16x16x32_bf16 v[68:71], v[144:147], v[198:201], v[68:71]
	v_mfma_f32_16x16x32_bf16 v[64:67], v[166:169], v[198:201], v[64:67]
	v_mfma_f32_16x16x32_bf16 v[124:127], v[162:165], v[178:181], v[124:127]
	v_mfma_f32_16x16x32_bf16 v[120:123], v[170:173], v[178:181], v[120:123]
	v_mfma_f32_16x16x32_bf16 v[100:103], v[162:165], v[186:189], v[100:103]
	v_mfma_f32_16x16x32_bf16 v[96:99], v[170:173], v[186:189], v[96:99]
	v_mfma_f32_16x16x32_bf16 v[84:87], v[162:165], v[194:197], v[84:87]
	v_mfma_f32_16x16x32_bf16 v[80:83], v[170:173], v[194:197], v[80:83]
	v_mfma_f32_16x16x32_bf16 v[68:71], v[162:165], v[202:205], v[68:71]
	v_mfma_f32_16x16x32_bf16 v[64:67], v[170:173], v[202:205], v[64:67]
	s_barrier
	s_add_i32 s0, s87, s68
	v_lshl_add_u64 v[206:207], s[64:65], 0, v[148:149]
	s_mov_b32 m0, s0
	ds_read_b128 v[174:177], v216 offset:16384
	ds_read_b128 v[178:181], v216 offset:17408
	ds_read_b128 v[182:185], v216 offset:18432
	ds_read_b128 v[186:189], v216 offset:19456
	ds_read_b128 v[190:193], v216 offset:20480
	ds_read_b128 v[194:197], v216 offset:21504
	ds_read_b128 v[198:201], v216 offset:22528
	ds_read_b128 v[202:205], v216 offset:23552
	global_load_lds_dwordx4 v[206:207], off
	s_add_i32 m0, s0, 0x2000
	s_add_u32 s0, s64, 0x80000
	v_lshl_add_u64 v[208:209], s[64:65], 0, v[150:151]
	s_addc_u32 s1, s65, 0
	s_add_i32 s14, s88, s68
	global_load_lds_dwordx4 v[208:209], off
	v_lshl_add_u64 v[220:221], s[0:1], 0, v[148:149]
	s_mov_b32 m0, s14
	v_lshl_add_u64 v[222:223], s[66:67], 0, v[150:151]
	global_load_lds_dwordx4 v[220:221], off
	v_lshl_add_u64 v[220:221], s[0:1], 0, v[150:151]
	s_add_i32 m0, s14, 0x2000
	s_nop 0
	global_load_lds_dwordx4 v[220:221], off
	v_lshl_add_u64 v[220:221], s[66:67], 0, v[148:149]
	s_mov_b32 m0, s69
	s_nop 0
	global_load_lds_dwordx4 v[220:221], off
	s_mov_b32 m0, s70
	s_nop 0
	global_load_lds_dwordx4 v[222:223], off
	s_waitcnt vmcnt(8)
	s_waitcnt lgkmcnt(0)
	s_barrier
	s_waitcnt lgkmcnt(0)
	v_mfma_f32_16x16x32_bf16 v[60:63], v[104:107], v[174:177], v[60:63]
	v_mfma_f32_16x16x32_bf16 v[56:59], v[136:139], v[174:177], v[56:59]
	v_mfma_f32_16x16x32_bf16 v[44:47], v[104:107], v[182:185], v[44:47]
	v_mfma_f32_16x16x32_bf16 v[40:43], v[136:139], v[182:185], v[40:43]
	v_mfma_f32_16x16x32_bf16 v[28:31], v[104:107], v[190:193], v[28:31]
	v_mfma_f32_16x16x32_bf16 v[24:27], v[136:139], v[190:193], v[24:27]
	v_mfma_f32_16x16x32_bf16 v[12:15], v[104:107], v[198:201], v[12:15]
	v_mfma_f32_16x16x32_bf16 v[8:11], v[136:139], v[198:201], v[8:11]
	v_mfma_f32_16x16x32_bf16 v[60:63], v[108:111], v[178:181], v[60:63]
	v_mfma_f32_16x16x32_bf16 v[56:59], v[140:143], v[178:181], v[56:59]
	v_mfma_f32_16x16x32_bf16 v[44:47], v[108:111], v[186:189], v[44:47]
	v_mfma_f32_16x16x32_bf16 v[40:43], v[140:143], v[186:189], v[40:43]
	v_mfma_f32_16x16x32_bf16 v[28:31], v[108:111], v[194:197], v[28:31]
	v_mfma_f32_16x16x32_bf16 v[24:27], v[140:143], v[194:197], v[24:27]
	v_mfma_f32_16x16x32_bf16 v[12:15], v[108:111], v[202:205], v[12:15]
	v_mfma_f32_16x16x32_bf16 v[8:11], v[140:143], v[202:205], v[8:11]
	v_mfma_f32_16x16x32_bf16 v[52:55], v[144:147], v[174:177], v[52:55]
	v_mfma_f32_16x16x32_bf16 v[48:51], v[166:169], v[174:177], v[48:51]
	v_mfma_f32_16x16x32_bf16 v[36:39], v[144:147], v[182:185], v[36:39]
	v_mfma_f32_16x16x32_bf16 v[32:35], v[166:169], v[182:185], v[32:35]
	v_mfma_f32_16x16x32_bf16 v[20:23], v[144:147], v[190:193], v[20:23]
	v_mfma_f32_16x16x32_bf16 v[16:19], v[166:169], v[190:193], v[16:19]
	v_mfma_f32_16x16x32_bf16 v[4:7], v[144:147], v[198:201], v[4:7]
	v_mfma_f32_16x16x32_bf16 v[0:3], v[166:169], v[198:201], v[0:3]
	v_mfma_f32_16x16x32_bf16 v[52:55], v[162:165], v[178:181], v[52:55]
	v_mfma_f32_16x16x32_bf16 v[48:51], v[170:173], v[178:181], v[48:51]
	v_mfma_f32_16x16x32_bf16 v[36:39], v[162:165], v[186:189], v[36:39]
	v_mfma_f32_16x16x32_bf16 v[32:35], v[170:173], v[186:189], v[32:35]
	v_mfma_f32_16x16x32_bf16 v[20:23], v[162:165], v[194:197], v[20:23]
	v_mfma_f32_16x16x32_bf16 v[16:19], v[170:173], v[194:197], v[16:19]
	v_mfma_f32_16x16x32_bf16 v[4:7], v[162:165], v[202:205], v[4:7]
	v_mfma_f32_16x16x32_bf16 v[0:3], v[170:173], v[202:205], v[0:3]
	s_barrier
	s_add_i32 s14, 0, 0x18000
	s_add_i32 s15, 0, 0x1c000
	v_add_u32_e32 v140, s14, v212
	v_add_u32_e32 v152, s15, v212
	ds_read_b128 v[104:107], v140
	ds_read_b128 v[108:111], v140 offset:1024
	ds_read_b128 v[136:139], v140 offset:2048
	ds_read_b128 v[140:143], v140 offset:3072
	ds_read_b128 v[144:147], v152
	ds_read_b128 v[162:165], v152 offset:1024
	ds_read_b128 v[166:169], v152 offset:2048
	ds_read_b128 v[170:173], v152 offset:3072
	s_add_u32 s0, s66, 0x80000
	s_addc_u32 s1, s67, 0
	s_mov_b32 m0, s71
	v_lshl_add_u64 v[224:225], s[0:1], 0, v[148:149]
	ds_read_b128 v[174:177], v216 offset:32768
	ds_read_b128 v[178:181], v216 offset:33792
	ds_read_b128 v[182:185], v216 offset:34816
	ds_read_b128 v[186:189], v216 offset:35840
	ds_read_b128 v[190:193], v216 offset:36864
	ds_read_b128 v[194:197], v216 offset:37888
	ds_read_b128 v[198:201], v216 offset:38912
	ds_read_b128 v[202:205], v216 offset:39936
	global_load_lds_dwordx4 v[224:225], off
	v_lshl_add_u64 v[224:225], s[0:1], 0, v[150:151]
	s_mov_b32 m0, s72
	s_nop 0
	global_load_lds_dwordx4 v[224:225], off
	s_waitcnt vmcnt(8)
	s_waitcnt lgkmcnt(0)
	s_barrier
	s_waitcnt lgkmcnt(0)
	v_mfma_f32_16x16x32_bf16 v[132:135], v[104:107], v[174:177], v[132:135]
	v_mfma_f32_16x16x32_bf16 v[128:131], v[136:139], v[174:177], v[128:131]
	v_mfma_f32_16x16x32_bf16 v[116:119], v[104:107], v[182:185], v[116:119]
	v_mfma_f32_16x16x32_bf16 v[112:115], v[136:139], v[182:185], v[112:115]
	v_mfma_f32_16x16x32_bf16 v[92:95], v[104:107], v[190:193], v[92:95]
	v_mfma_f32_16x16x32_bf16 v[88:91], v[136:139], v[190:193], v[88:91]
	v_mfma_f32_16x16x32_bf16 v[76:79], v[104:107], v[198:201], v[76:79]
	v_mfma_f32_16x16x32_bf16 v[72:75], v[136:139], v[198:201], v[72:75]
	v_mfma_f32_16x16x32_bf16 v[132:135], v[108:111], v[178:181], v[132:135]
	v_mfma_f32_16x16x32_bf16 v[128:131], v[140:143], v[178:181], v[128:131]
	v_mfma_f32_16x16x32_bf16 v[116:119], v[108:111], v[186:189], v[116:119]
	v_mfma_f32_16x16x32_bf16 v[112:115], v[140:143], v[186:189], v[112:115]
	v_mfma_f32_16x16x32_bf16 v[92:95], v[108:111], v[194:197], v[92:95]
	v_mfma_f32_16x16x32_bf16 v[88:91], v[140:143], v[194:197], v[88:91]
	v_mfma_f32_16x16x32_bf16 v[76:79], v[108:111], v[202:205], v[76:79]
	v_mfma_f32_16x16x32_bf16 v[72:75], v[140:143], v[202:205], v[72:75]
	v_mfma_f32_16x16x32_bf16 v[124:127], v[144:147], v[174:177], v[124:127]
	v_mfma_f32_16x16x32_bf16 v[120:123], v[166:169], v[174:177], v[120:123]
	v_mfma_f32_16x16x32_bf16 v[100:103], v[144:147], v[182:185], v[100:103]
	v_mfma_f32_16x16x32_bf16 v[96:99], v[166:169], v[182:185], v[96:99]
	v_mfma_f32_16x16x32_bf16 v[84:87], v[144:147], v[190:193], v[84:87]
	v_mfma_f32_16x16x32_bf16 v[80:83], v[166:169], v[190:193], v[80:83]
	v_mfma_f32_16x16x32_bf16 v[68:71], v[144:147], v[198:201], v[68:71]
	v_mfma_f32_16x16x32_bf16 v[64:67], v[166:169], v[198:201], v[64:67]
	v_mfma_f32_16x16x32_bf16 v[124:127], v[162:165], v[178:181], v[124:127]
	v_mfma_f32_16x16x32_bf16 v[120:123], v[170:173], v[178:181], v[120:123]
	v_mfma_f32_16x16x32_bf16 v[100:103], v[162:165], v[186:189], v[100:103]
	v_mfma_f32_16x16x32_bf16 v[96:99], v[170:173], v[186:189], v[96:99]
	v_mfma_f32_16x16x32_bf16 v[84:87], v[162:165], v[194:197], v[84:87]
	v_mfma_f32_16x16x32_bf16 v[80:83], v[170:173], v[194:197], v[80:83]
	v_mfma_f32_16x16x32_bf16 v[68:71], v[162:165], v[202:205], v[68:71]
	v_mfma_f32_16x16x32_bf16 v[64:67], v[170:173], v[202:205], v[64:67]
	s_barrier
	s_add_i32 s0, s14, s68
	v_lshl_add_u64 v[206:207], v[206:207], 0, s[46:47]
	s_mov_b32 m0, s0
	ds_read_b128 v[174:177], v216 offset:49152
	ds_read_b128 v[178:181], v216 offset:50176
	ds_read_b128 v[182:185], v216 offset:51200
	ds_read_b128 v[186:189], v216 offset:52224
	ds_read_b128 v[190:193], v216 offset:53248
	ds_read_b128 v[194:197], v216 offset:54272
	ds_read_b128 v[198:201], v216 offset:55296
	ds_read_b128 v[202:205], v216 offset:56320
	global_load_lds_dwordx4 v[206:207], off
	s_add_i32 m0, s0, 0x2000
	s_add_u32 s0, s64, 0x80080
	v_lshl_add_u64 v[206:207], v[208:209], 0, s[46:47]
	s_addc_u32 s1, s65, 0
	s_add_i32 s14, s15, s68
	global_load_lds_dwordx4 v[206:207], off
	v_lshl_add_u64 v[206:207], s[0:1], 0, v[148:149]
	s_mov_b32 m0, s14
	s_nop 0
	global_load_lds_dwordx4 v[206:207], off
	v_lshl_add_u64 v[206:207], s[0:1], 0, v[150:151]
	s_add_i32 m0, s14, 0x2000
	s_nop 0
	global_load_lds_dwordx4 v[206:207], off
	v_lshl_add_u64 v[206:207], v[220:221], 0, s[46:47]
	s_mov_b32 m0, s78
	s_nop 0
	global_load_lds_dwordx4 v[206:207], off
	v_lshl_add_u64 v[206:207], v[222:223], 0, s[46:47]
	s_mov_b32 m0, s79
	s_nop 0
	global_load_lds_dwordx4 v[206:207], off
	s_waitcnt vmcnt(8)
	s_waitcnt lgkmcnt(0)
	s_barrier
	s_waitcnt lgkmcnt(0)
	v_mfma_f32_16x16x32_bf16 v[60:63], v[104:107], v[174:177], v[60:63]
	v_mfma_f32_16x16x32_bf16 v[56:59], v[136:139], v[174:177], v[56:59]
	v_mfma_f32_16x16x32_bf16 v[44:47], v[104:107], v[182:185], v[44:47]
	v_mfma_f32_16x16x32_bf16 v[40:43], v[136:139], v[182:185], v[40:43]
	v_mfma_f32_16x16x32_bf16 v[28:31], v[104:107], v[190:193], v[28:31]
	v_mfma_f32_16x16x32_bf16 v[24:27], v[136:139], v[190:193], v[24:27]
	v_mfma_f32_16x16x32_bf16 v[12:15], v[104:107], v[198:201], v[12:15]
	v_mfma_f32_16x16x32_bf16 v[8:11], v[136:139], v[198:201], v[8:11]
	v_mfma_f32_16x16x32_bf16 v[60:63], v[108:111], v[178:181], v[60:63]
	v_mfma_f32_16x16x32_bf16 v[56:59], v[140:143], v[178:181], v[56:59]
	v_mfma_f32_16x16x32_bf16 v[44:47], v[108:111], v[186:189], v[44:47]
	v_mfma_f32_16x16x32_bf16 v[40:43], v[140:143], v[186:189], v[40:43]
	v_mfma_f32_16x16x32_bf16 v[28:31], v[108:111], v[194:197], v[28:31]
	v_mfma_f32_16x16x32_bf16 v[24:27], v[140:143], v[194:197], v[24:27]
	v_mfma_f32_16x16x32_bf16 v[12:15], v[108:111], v[202:205], v[12:15]
	v_mfma_f32_16x16x32_bf16 v[8:11], v[140:143], v[202:205], v[8:11]
	v_mfma_f32_16x16x32_bf16 v[52:55], v[144:147], v[174:177], v[52:55]
	v_mfma_f32_16x16x32_bf16 v[48:51], v[166:169], v[174:177], v[48:51]
	v_mfma_f32_16x16x32_bf16 v[36:39], v[144:147], v[182:185], v[36:39]
	v_mfma_f32_16x16x32_bf16 v[32:35], v[166:169], v[182:185], v[32:35]
	v_mfma_f32_16x16x32_bf16 v[20:23], v[144:147], v[190:193], v[20:23]
	v_mfma_f32_16x16x32_bf16 v[16:19], v[166:169], v[190:193], v[16:19]
	v_mfma_f32_16x16x32_bf16 v[4:7], v[144:147], v[198:201], v[4:7]
	v_mfma_f32_16x16x32_bf16 v[0:3], v[166:169], v[198:201], v[0:3]
	v_mfma_f32_16x16x32_bf16 v[52:55], v[162:165], v[178:181], v[52:55]
	v_mfma_f32_16x16x32_bf16 v[48:51], v[170:173], v[178:181], v[48:51]
	v_mfma_f32_16x16x32_bf16 v[36:39], v[162:165], v[186:189], v[36:39]
	v_mfma_f32_16x16x32_bf16 v[32:35], v[170:173], v[186:189], v[32:35]
	v_mfma_f32_16x16x32_bf16 v[20:23], v[162:165], v[194:197], v[20:23]
	v_mfma_f32_16x16x32_bf16 v[16:19], v[170:173], v[194:197], v[16:19]
	v_mfma_f32_16x16x32_bf16 v[4:7], v[162:165], v[202:205], v[4:7]
	v_mfma_f32_16x16x32_bf16 v[0:3], v[170:173], v[202:205], v[0:3]
	s_barrier
	s_add_i32 s97, s97, 2
	s_add_u32 s62, s62, 0x100
	s_addc_u32 s63, s63, 0
	s_add_u32 s95, s95, 0x100
	s_addc_u32 s96, s96, 0
	s_cmp_gt_u32 s97, 29
	s_cbranch_scc0 .LBB0_199
	s_and_b64 vcc, exec, s[48:49]
	s_cbranch_vccz .LBB0_202
	s_barrier

.LBB0_605:
	s_lshl_b32 s0, s0, 5
	s_add_i32 s74, 0, 0x18000
	s_and_b32 s39, s0, 0x60
	s_add_i32 s77, s74, s68
	s_lshl_b32 s47, s46, 13
	s_lshl_b32 s69, s39, 7
	v_lshl_add_u64 v[18:19], v[0:1], 0, s[58:59]
	s_mov_b32 m0, s77
	s_add_i32 s0, s77, 0x2000
	s_add_i32 s78, s62, 0x8000
	s_add_i32 s1, s62, 0xa000
	s_waitcnt vmcnt(2)
	s_barrier
	global_load_lds_dwordx4 v[18:19], off
	v_lshl_add_u64 v[20:21], v[2:3], 0, s[58:59]
	s_mov_b32 m0, s0
	s_add_u32 s72, s66, 0x10080
	global_load_lds_dwordx4 v[20:21], off
	v_lshl_add_u64 v[16:17], v[14:15], 0, s[58:59]
	s_mov_b32 m0, s78
	s_addc_u32 s73, s67, 0
	s_add_i32 s75, 0, 0x1c000
	global_load_lds_dwordx4 v[16:17], off
	v_lshl_add_u64 v[22:23], v[24:25], 0, s[58:59]
	s_mov_b32 m0, s1
	s_add_i32 s14, s75, s68
	global_load_lds_dwordx4 v[22:23], off
	v_lshl_add_u64 v[28:29], s[72:73], 0, v[144:145]
	s_mov_b32 m0, s14
	s_add_i32 s15, s14, 0x2000
	global_load_lds_dwordx4 v[28:29], off
	v_lshl_add_u64 v[30:31], s[72:73], 0, v[32:33]
	s_mov_b32 m0, s15
	v_bfe_u32 v36, v34, 4, 2
	global_load_lds_dwordx4 v[30:31], off
	v_and_b32_e32 v35, 15, v34
	v_lshlrev_b32_e32 v37, 4, v36
	v_lshlrev_b32_e32 v34, 2, v34
	v_lshl_or_b32 v146, s46, 6, v35
	v_lshl_or_b32 v35, v35, 6, v37
	v_and_b32_e32 v34, 32, v34
	v_bitop3_b32 v37, v35, s47, v34 bitop3:0xde
	v_bitop3_b32 v34, v35, s69, v34 bitop3:0xde
	s_add_i32 s47, 0, 0x10000
	s_add_i32 s94, 0, 0x14000
	v_add_u32_e32 v142, s47, v34
	s_add_u32 s92, s70, 0x40080
	s_waitcnt vmcnt(6)
	s_barrier
	v_add_u32_e32 v143, s94, v34
	s_addc_u32 s93, s71, 0
	s_add_i32 s47, s47, s68
	ds_read_b128 v[38:41], v142
	ds_read_b128 v[42:45], v142 offset:1024
	ds_read_b128 v[46:49], v142 offset:2048
	ds_read_b128 v[50:53], v142 offset:3072
	ds_read_b128 v[54:57], v143
	ds_read_b128 v[58:61], v143 offset:1024
	ds_read_b128 v[62:65], v143 offset:2048
	ds_read_b128 v[66:69], v143 offset:3072
	s_add_i32 s90, s62, 0xc000
	s_add_i32 s89, s62, 0xe000
	s_add_i32 s46, s47, 0x2000
	v_add_u32_e32 v147, s74, v34
	s_add_u32 s74, s66, 0x10100
	v_add_u32_e32 v152, s75, v34
	s_addc_u32 s75, s67, 0
	s_add_i32 s94, s94, s68
	s_add_i32 s87, s94, 0x2000
	s_add_u32 s72, s70, 0x40100
	s_addc_u32 s73, s71, 0
	s_add_u32 s68, s66, 0x10180
	s_addc_u32 s69, s67, 0
	s_add_u32 s66, s70, 0x40180
	s_addc_u32 s67, s71, 0
	v_add_u32_e32 v37, 0, v37
	s_cmpk_gt_u32 s88, 0xff
	s_mov_b32 m0, s90
	v_lshl_add_u64 v[34:35], s[92:93], 0, v[26:27]
	ds_read_b128 v[70:73], v37
	ds_read_b128 v[74:77], v37 offset:1024
	ds_read_b128 v[78:81], v37 offset:2048
	ds_read_b128 v[82:85], v37 offset:3072
	ds_read_b128 v[86:89], v37 offset:4096
	ds_read_b128 v[90:93], v37 offset:5120
	ds_read_b128 v[94:97], v37 offset:6144
	ds_read_b128 v[98:101], v37 offset:7168
	global_load_lds_dwordx4 v[34:35], off
	v_lshl_add_u64 v[34:35], s[92:93], 0, v[8:9]
	s_mov_b32 m0, s89
	s_nop 0
	global_load_lds_dwordx4 v[34:35], off
	s_waitcnt vmcnt(8)
	s_waitcnt lgkmcnt(0)
	s_barrier
	s_waitcnt lgkmcnt(0)
	v_mfma_f32_16x16x32_bf16 v[102:105], v[38:41], v[70:73], 0
	v_mfma_f32_16x16x32_bf16 v[106:109], v[46:49], v[70:73], 0
	v_mfma_f32_16x16x32_bf16 v[110:113], v[38:41], v[78:81], 0
	v_mfma_f32_16x16x32_bf16 v[114:117], v[46:49], v[78:81], 0
	v_mfma_f32_16x16x32_bf16 v[118:121], v[38:41], v[86:89], 0
	v_mfma_f32_16x16x32_bf16 v[122:125], v[46:49], v[86:89], 0
	v_mfma_f32_16x16x32_bf16 v[126:129], v[38:41], v[94:97], 0
	v_mfma_f32_16x16x32_bf16 v[130:133], v[46:49], v[94:97], 0
	v_mfma_f32_16x16x32_bf16 v[102:105], v[42:45], v[74:77], v[102:105]
	v_mfma_f32_16x16x32_bf16 v[106:109], v[50:53], v[74:77], v[106:109]
	v_mfma_f32_16x16x32_bf16 v[110:113], v[42:45], v[82:85], v[110:113]
	v_mfma_f32_16x16x32_bf16 v[114:117], v[50:53], v[82:85], v[114:117]
	v_mfma_f32_16x16x32_bf16 v[118:121], v[42:45], v[90:93], v[118:121]
	v_mfma_f32_16x16x32_bf16 v[122:125], v[50:53], v[90:93], v[122:125]
	v_mfma_f32_16x16x32_bf16 v[126:129], v[42:45], v[98:101], v[126:129]
	v_mfma_f32_16x16x32_bf16 v[130:133], v[50:53], v[98:101], v[130:133]
	v_mfma_f32_16x16x32_bf16 v[134:137], v[54:57], v[70:73], 0
	v_mfma_f32_16x16x32_bf16 v[70:73], v[62:65], v[70:73], 0
	v_mfma_f32_16x16x32_bf16 v[134:137], v[58:61], v[74:77], v[134:137]
	v_mfma_f32_16x16x32_bf16 v[70:73], v[66:69], v[74:77], v[70:73]
	v_mfma_f32_16x16x32_bf16 v[74:77], v[54:57], v[78:81], 0
	v_mfma_f32_16x16x32_bf16 v[78:81], v[62:65], v[78:81], 0
	v_mfma_f32_16x16x32_bf16 v[74:77], v[58:61], v[82:85], v[74:77]
	v_mfma_f32_16x16x32_bf16 v[78:81], v[66:69], v[82:85], v[78:81]
	v_mfma_f32_16x16x32_bf16 v[82:85], v[54:57], v[86:89], 0
	v_mfma_f32_16x16x32_bf16 v[86:89], v[62:65], v[86:89], 0
	v_mfma_f32_16x16x32_bf16 v[82:85], v[58:61], v[90:93], v[82:85]
	v_mfma_f32_16x16x32_bf16 v[86:89], v[66:69], v[90:93], v[86:89]
	v_mfma_f32_16x16x32_bf16 v[90:93], v[54:57], v[94:97], 0
	v_mfma_f32_16x16x32_bf16 v[94:97], v[62:65], v[94:97], 0
	v_mfma_f32_16x16x32_bf16 v[90:93], v[58:61], v[98:101], v[90:93]
	v_mfma_f32_16x16x32_bf16 v[94:97], v[66:69], v[98:101], v[94:97]
	s_barrier
	s_mov_b32 m0, s47
	v_lshl_add_u64 v[34:35], v[0:1], 0, s[56:57]
	ds_read_b128 v[98:101], v37 offset:16384
	ds_read_b128 v[138:141], v37 offset:17408
	ds_read_b128 v[148:151], v37 offset:18432
	ds_read_b128 v[156:159], v37 offset:19456
	ds_read_b128 v[160:163], v37 offset:20480
	ds_read_b128 v[164:167], v37 offset:21504
	ds_read_b128 v[168:171], v37 offset:22528
	ds_read_b128 v[172:175], v37 offset:23552
	global_load_lds_dwordx4 v[34:35], off
	v_lshl_add_u64 v[34:35], v[2:3], 0, s[56:57]
	s_mov_b32 m0, s46
	s_nop 0
	global_load_lds_dwordx4 v[34:35], off
	v_lshl_add_u64 v[34:35], s[74:75], 0, v[144:145]
	s_mov_b32 m0, s94
	s_nop 0
	global_load_lds_dwordx4 v[34:35], off
	v_lshl_add_u64 v[34:35], s[74:75], 0, v[32:33]
	s_mov_b32 m0, s87
	s_nop 0
	global_load_lds_dwordx4 v[34:35], off
	v_lshl_add_u64 v[34:35], v[14:15], 0, s[56:57]
	s_mov_b32 m0, s62
	s_nop 0
	global_load_lds_dwordx4 v[34:35], off
	v_lshl_add_u64 v[34:35], v[24:25], 0, s[56:57]
	s_mov_b32 m0, s8
	s_nop 0
	global_load_lds_dwordx4 v[34:35], off
	s_waitcnt vmcnt(8)
	s_waitcnt lgkmcnt(0)
	s_barrier
	s_waitcnt lgkmcnt(0)
	v_mfma_f32_16x16x32_bf16 v[176:179], v[38:41], v[98:101], 0
	v_mfma_f32_16x16x32_bf16 v[184:187], v[38:41], v[148:151], 0
	v_mfma_f32_16x16x32_bf16 v[192:195], v[38:41], v[160:163], 0
	v_mfma_f32_16x16x32_bf16 v[38:41], v[38:41], v[168:171], 0
	v_mfma_f32_16x16x32_bf16 v[176:179], v[42:45], v[138:141], v[176:179]
	v_mfma_f32_16x16x32_bf16 v[184:187], v[42:45], v[156:159], v[184:187]
	v_mfma_f32_16x16x32_bf16 v[192:195], v[42:45], v[164:167], v[192:195]
	v_mfma_f32_16x16x32_bf16 v[38:41], v[42:45], v[172:175], v[38:41]
	v_mfma_f32_16x16x32_bf16 v[42:45], v[46:49], v[168:171], 0
	v_mfma_f32_16x16x32_bf16 v[180:183], v[46:49], v[98:101], 0
	v_mfma_f32_16x16x32_bf16 v[188:191], v[46:49], v[148:151], 0
	v_mfma_f32_16x16x32_bf16 v[196:199], v[46:49], v[160:163], 0
	v_mfma_f32_16x16x32_bf16 v[42:45], v[50:53], v[172:175], v[42:45]
	v_mfma_f32_16x16x32_bf16 v[180:183], v[50:53], v[138:141], v[180:183]
	v_mfma_f32_16x16x32_bf16 v[188:191], v[50:53], v[156:159], v[188:191]
	v_mfma_f32_16x16x32_bf16 v[196:199], v[50:53], v[164:167], v[196:199]
	v_mfma_f32_16x16x32_bf16 v[46:49], v[54:57], v[98:101], 0
	v_mfma_f32_16x16x32_bf16 v[50:53], v[62:65], v[98:101], 0
	v_mfma_f32_16x16x32_bf16 v[46:49], v[58:61], v[138:141], v[46:49]
	v_mfma_f32_16x16x32_bf16 v[50:53], v[66:69], v[138:141], v[50:53]
	v_mfma_f32_16x16x32_bf16 v[98:101], v[54:57], v[148:151], 0
	v_mfma_f32_16x16x32_bf16 v[138:141], v[62:65], v[148:151], 0
	v_mfma_f32_16x16x32_bf16 v[148:151], v[54:57], v[160:163], 0
	v_mfma_f32_16x16x32_bf16 v[54:57], v[54:57], v[168:171], 0
	v_mfma_f32_16x16x32_bf16 v[98:101], v[58:61], v[156:159], v[98:101]
	v_mfma_f32_16x16x32_bf16 v[148:151], v[58:61], v[164:167], v[148:151]
	v_mfma_f32_16x16x32_bf16 v[54:57], v[58:61], v[172:175], v[54:57]
	v_mfma_f32_16x16x32_bf16 v[58:61], v[62:65], v[168:171], 0
	v_mfma_f32_16x16x32_bf16 v[138:141], v[66:69], v[156:159], v[138:141]
	v_mfma_f32_16x16x32_bf16 v[156:159], v[62:65], v[160:163], 0
	v_mfma_f32_16x16x32_bf16 v[58:61], v[66:69], v[172:175], v[58:61]
	v_mfma_f32_16x16x32_bf16 v[156:159], v[66:69], v[164:167], v[156:159]
	s_barrier
	ds_read_b128 v[62:65], v147
	ds_read_b128 v[66:69], v147 offset:1024
	ds_read_b128 v[160:163], v147 offset:2048
	ds_read_b128 v[164:167], v147 offset:3072
	ds_read_b128 v[168:171], v152
	ds_read_b128 v[172:175], v152 offset:1024
	ds_read_b128 v[200:203], v152 offset:2048
	ds_read_b128 v[204:207], v152 offset:3072
	s_mov_b32 m0, vcc_lo
	v_lshl_add_u64 v[34:35], s[72:73], 0, v[26:27]
	ds_read_b128 v[208:211], v37 offset:32768
	ds_read_b128 v[216:219], v37 offset:33792
	ds_read_b128 v[220:223], v37 offset:34816
	ds_read_b128 v[224:227], v37 offset:35840
	ds_read_b128 v[228:231], v37 offset:36864
	ds_read_b128 v[232:235], v37 offset:37888
	ds_read_b128 v[236:239], v37 offset:38912
	ds_read_b128 v[240:243], v37 offset:39936
	global_load_lds_dwordx4 v[34:35], off
	v_lshl_add_u64 v[34:35], s[72:73], 0, v[8:9]
	s_mov_b32 m0, vcc_hi
	s_nop 0
	global_load_lds_dwordx4 v[34:35], off
	s_waitcnt vmcnt(8)
	s_waitcnt lgkmcnt(0)
	s_barrier
	s_waitcnt lgkmcnt(0)
	v_mfma_f32_16x16x32_bf16 v[102:105], v[62:65], v[208:211], v[102:105]
	v_mfma_f32_16x16x32_bf16 v[106:109], v[160:163], v[208:211], v[106:109]
	v_mfma_f32_16x16x32_bf16 v[110:113], v[62:65], v[220:223], v[110:113]
	v_mfma_f32_16x16x32_bf16 v[114:117], v[160:163], v[220:223], v[114:117]
	v_mfma_f32_16x16x32_bf16 v[118:121], v[62:65], v[228:231], v[118:121]
	v_mfma_f32_16x16x32_bf16 v[122:125], v[160:163], v[228:231], v[122:125]
	v_mfma_f32_16x16x32_bf16 v[126:129], v[62:65], v[236:239], v[126:129]
	v_mfma_f32_16x16x32_bf16 v[130:133], v[160:163], v[236:239], v[130:133]
	v_mfma_f32_16x16x32_bf16 v[102:105], v[66:69], v[216:219], v[102:105]
	v_mfma_f32_16x16x32_bf16 v[106:109], v[164:167], v[216:219], v[106:109]
	v_mfma_f32_16x16x32_bf16 v[110:113], v[66:69], v[224:227], v[110:113]
	v_mfma_f32_16x16x32_bf16 v[114:117], v[164:167], v[224:227], v[114:117]
	v_mfma_f32_16x16x32_bf16 v[118:121], v[66:69], v[232:235], v[118:121]
	v_mfma_f32_16x16x32_bf16 v[122:125], v[164:167], v[232:235], v[122:125]
	v_mfma_f32_16x16x32_bf16 v[126:129], v[66:69], v[240:243], v[126:129]
	v_mfma_f32_16x16x32_bf16 v[130:133], v[164:167], v[240:243], v[130:133]
	v_mfma_f32_16x16x32_bf16 v[134:137], v[168:171], v[208:211], v[134:137]
	v_mfma_f32_16x16x32_bf16 v[70:73], v[200:203], v[208:211], v[70:73]
	v_mfma_f32_16x16x32_bf16 v[74:77], v[168:171], v[220:223], v[74:77]
	v_mfma_f32_16x16x32_bf16 v[78:81], v[200:203], v[220:223], v[78:81]
	v_mfma_f32_16x16x32_bf16 v[82:85], v[168:171], v[228:231], v[82:85]
	v_mfma_f32_16x16x32_bf16 v[86:89], v[200:203], v[228:231], v[86:89]
	v_mfma_f32_16x16x32_bf16 v[90:93], v[168:171], v[236:239], v[90:93]
	v_mfma_f32_16x16x32_bf16 v[94:97], v[200:203], v[236:239], v[94:97]
	v_mfma_f32_16x16x32_bf16 v[134:137], v[172:175], v[216:219], v[134:137]
	v_mfma_f32_16x16x32_bf16 v[70:73], v[204:207], v[216:219], v[70:73]
	v_mfma_f32_16x16x32_bf16 v[74:77], v[172:175], v[224:227], v[74:77]
	v_mfma_f32_16x16x32_bf16 v[78:81], v[204:207], v[224:227], v[78:81]
	v_mfma_f32_16x16x32_bf16 v[82:85], v[172:175], v[232:235], v[82:85]
	v_mfma_f32_16x16x32_bf16 v[86:89], v[204:207], v[232:235], v[86:89]
	v_mfma_f32_16x16x32_bf16 v[90:93], v[172:175], v[240:243], v[90:93]
	v_mfma_f32_16x16x32_bf16 v[94:97], v[204:207], v[240:243], v[94:97]
	s_barrier
	s_mov_b32 m0, s77
	v_lshl_add_u64 v[34:35], v[0:1], 0, s[60:61]
	ds_read_b128 v[208:211], v37 offset:49152
	ds_read_b128 v[216:219], v37 offset:50176
	ds_read_b128 v[220:223], v37 offset:51200
	ds_read_b128 v[224:227], v37 offset:52224
	ds_read_b128 v[228:231], v37 offset:53248
	ds_read_b128 v[232:235], v37 offset:54272
	ds_read_b128 v[236:239], v37 offset:55296
	ds_read_b128 v[240:243], v37 offset:56320
	global_load_lds_dwordx4 v[34:35], off
	v_lshl_add_u64 v[34:35], v[2:3], 0, s[60:61]
	s_mov_b32 m0, s0
	v_lshl_add_u64 v[32:33], s[68:69], 0, v[32:33]
	global_load_lds_dwordx4 v[34:35], off
	v_lshl_add_u64 v[34:35], s[68:69], 0, v[144:145]
	s_mov_b32 m0, s14
	s_nop 0
	global_load_lds_dwordx4 v[34:35], off
	s_mov_b32 m0, s15
	s_nop 0
	global_load_lds_dwordx4 v[32:33], off
	v_lshl_add_u64 v[32:33], v[14:15], 0, s[60:61]
	s_mov_b32 m0, s78
	s_nop 0
	global_load_lds_dwordx4 v[32:33], off
	v_lshl_add_u64 v[32:33], v[24:25], 0, s[60:61]
	s_mov_b32 m0, s1
	s_nop 0
	global_load_lds_dwordx4 v[32:33], off
	s_waitcnt vmcnt(8)
	s_waitcnt lgkmcnt(0)
	s_barrier
	s_waitcnt lgkmcnt(0)
	v_mfma_f32_16x16x32_bf16 v[32:35], v[62:65], v[208:211], v[176:179]
	v_mfma_f32_16x16x32_bf16 v[38:41], v[62:65], v[236:239], v[38:41]
	v_mfma_f32_16x16x32_bf16 v[42:45], v[160:163], v[236:239], v[42:45]
	v_mfma_f32_16x16x32_bf16 v[32:35], v[66:69], v[216:219], v[32:35]
	v_mfma_f32_16x16x32_bf16 v[176:179], v[160:163], v[208:211], v[180:183]
	v_mfma_f32_16x16x32_bf16 v[180:183], v[62:65], v[220:223], v[184:187]
	v_mfma_f32_16x16x32_bf16 v[184:187], v[160:163], v[220:223], v[188:191]
	v_mfma_f32_16x16x32_bf16 v[188:191], v[62:65], v[228:231], v[192:195]
	v_mfma_f32_16x16x32_bf16 v[192:195], v[160:163], v[228:231], v[196:199]
	v_mfma_f32_16x16x32_bf16 v[38:41], v[66:69], v[240:243], v[38:41]
	v_mfma_f32_16x16x32_bf16 v[42:45], v[164:167], v[240:243], v[42:45]
	v_mfma_f32_16x16x32_bf16 v[176:179], v[164:167], v[216:219], v[176:179]
	v_mfma_f32_16x16x32_bf16 v[180:183], v[66:69], v[224:227], v[180:183]
	v_mfma_f32_16x16x32_bf16 v[184:187], v[164:167], v[224:227], v[184:187]
	v_mfma_f32_16x16x32_bf16 v[188:191], v[66:69], v[232:235], v[188:191]
	v_mfma_f32_16x16x32_bf16 v[192:195], v[164:167], v[232:235], v[192:195]
	v_mfma_f32_16x16x32_bf16 v[46:49], v[168:171], v[208:211], v[46:49]
	v_mfma_f32_16x16x32_bf16 v[50:53], v[200:203], v[208:211], v[50:53]
	v_mfma_f32_16x16x32_bf16 v[62:65], v[168:171], v[220:223], v[98:101]
	v_mfma_f32_16x16x32_bf16 v[66:69], v[200:203], v[220:223], v[138:141]
	v_mfma_f32_16x16x32_bf16 v[98:101], v[168:171], v[228:231], v[148:151]
	v_mfma_f32_16x16x32_bf16 v[138:141], v[200:203], v[228:231], v[156:159]
	v_mfma_f32_16x16x32_bf16 v[54:57], v[168:171], v[236:239], v[54:57]
	v_mfma_f32_16x16x32_bf16 v[58:61], v[200:203], v[236:239], v[58:61]
	v_mfma_f32_16x16x32_bf16 v[46:49], v[172:175], v[216:219], v[46:49]
	v_mfma_f32_16x16x32_bf16 v[50:53], v[204:207], v[216:219], v[50:53]
	v_mfma_f32_16x16x32_bf16 v[62:65], v[172:175], v[224:227], v[62:65]
	v_mfma_f32_16x16x32_bf16 v[66:69], v[204:207], v[224:227], v[66:69]
	v_mfma_f32_16x16x32_bf16 v[98:101], v[172:175], v[232:235], v[98:101]
	v_mfma_f32_16x16x32_bf16 v[138:141], v[204:207], v[232:235], v[138:141]
	v_mfma_f32_16x16x32_bf16 v[54:57], v[172:175], v[240:243], v[54:57]
	v_mfma_f32_16x16x32_bf16 v[58:61], v[204:207], v[240:243], v[58:61]
	s_barrier
	ds_read_b128 v[148:151], v142
	ds_read_b128 v[156:159], v142 offset:1024
	ds_read_b128 v[160:163], v142 offset:2048
	ds_read_b128 v[164:167], v142 offset:3072
	ds_read_b128 v[168:171], v143
	ds_read_b128 v[172:175], v143 offset:1024
	ds_read_b128 v[196:199], v143 offset:2048
	ds_read_b128 v[200:203], v143 offset:3072
	s_mov_b32 m0, s90
	v_lshl_add_u64 v[26:27], s[66:67], 0, v[26:27]
	ds_read_b128 v[204:207], v37
	ds_read_b128 v[208:211], v37 offset:1024
	ds_read_b128 v[216:219], v37 offset:2048
	ds_read_b128 v[220:223], v37 offset:3072
	ds_read_b128 v[224:227], v37 offset:4096
	ds_read_b128 v[228:231], v37 offset:5120
	ds_read_b128 v[232:235], v37 offset:6144
	ds_read_b128 v[236:239], v37 offset:7168
	global_load_lds_dwordx4 v[26:27], off
	v_lshl_add_u64 v[8:9], s[66:67], 0, v[8:9]
	s_mov_b32 m0, s89
	s_nop 0
	global_load_lds_dwordx4 v[8:9], off
	s_waitcnt vmcnt(8)
	s_waitcnt lgkmcnt(0)
	s_barrier
	s_waitcnt lgkmcnt(0)
	v_mfma_f32_16x16x32_bf16 v[114:117], v[160:163], v[216:219], v[114:117]
	v_mfma_f32_16x16x32_bf16 v[240:243], v[164:167], v[220:223], v[114:117]
	v_mfma_f32_16x16x32_bf16 v[114:117], v[148:151], v[224:227], v[118:121]
	v_mfma_f32_16x16x32_bf16 v[244:247], v[156:159], v[228:231], v[114:117]
	v_mfma_f32_16x16x32_bf16 v[114:117], v[160:163], v[224:227], v[122:125]
	v_mfma_f32_16x16x32_bf16 v[248:251], v[164:167], v[228:231], v[114:117]
	v_mfma_f32_16x16x32_bf16 v[114:117], v[148:151], v[232:235], v[126:129]
	v_mfma_f32_16x16x32_bf16 v[102:105], v[148:151], v[204:207], v[102:105]
	v_mfma_f32_16x16x32_bf16 v[106:109], v[160:163], v[204:207], v[106:109]
	v_mfma_f32_16x16x32_bf16 v[110:113], v[148:151], v[216:219], v[110:113]
	v_mfma_f32_16x16x32_bf16 v[212:215], v[156:159], v[236:239], v[114:117]
	v_mfma_f32_16x16x32_bf16 v[114:117], v[160:163], v[232:235], v[130:133]
	v_mfma_f32_16x16x32_bf16 v[102:105], v[156:159], v[208:211], v[102:105]
	v_mfma_f32_16x16x32_bf16 v[106:109], v[164:167], v[208:211], v[106:109]
	v_mfma_f32_16x16x32_bf16 v[110:113], v[156:159], v[220:223], v[110:113]
	v_mfma_f32_16x16x32_bf16 v[128:131], v[164:167], v[236:239], v[114:117]
	v_mfma_f32_16x16x32_bf16 v[78:81], v[196:199], v[216:219], v[78:81]
	v_mfma_f32_16x16x32_bf16 v[114:117], v[168:171], v[204:207], v[134:137]
	v_mfma_f32_16x16x32_bf16 v[70:73], v[196:199], v[204:207], v[70:73]
	v_mfma_f32_16x16x32_bf16 v[204:207], v[200:203], v[220:223], v[78:81]
	v_mfma_f32_16x16x32_bf16 v[78:81], v[168:171], v[224:227], v[82:85]
	v_mfma_f32_16x16x32_bf16 v[132:135], v[172:175], v[208:211], v[114:117]
	v_mfma_f32_16x16x32_bf16 v[70:73], v[200:203], v[208:211], v[70:73]
	v_mfma_f32_16x16x32_bf16 v[208:211], v[172:175], v[228:231], v[78:81]
	v_mfma_f32_16x16x32_bf16 v[78:81], v[196:199], v[224:227], v[86:89]
	v_mfma_f32_16x16x32_bf16 v[84:87], v[200:203], v[228:231], v[78:81]
	v_mfma_f32_16x16x32_bf16 v[78:81], v[168:171], v[232:235], v[90:93]
	v_mfma_f32_16x16x32_bf16 v[74:77], v[168:171], v[216:219], v[74:77]
	v_mfma_f32_16x16x32_bf16 v[88:91], v[172:175], v[236:239], v[78:81]
	v_mfma_f32_16x16x32_bf16 v[78:81], v[196:199], v[232:235], v[94:97]
	v_mfma_f32_16x16x32_bf16 v[74:77], v[172:175], v[220:223], v[74:77]
	v_mfma_f32_16x16x32_bf16 v[92:95], v[200:203], v[236:239], v[78:81]
	s_barrier
	s_mov_b32 m0, s47
	s_nop 2
	ds_read_b128 v[78:81], v37 offset:16384
	ds_read_b128 v[114:117], v37 offset:17408
	ds_read_b128 v[118:121], v37 offset:18432
	ds_read_b128 v[122:125], v37 offset:19456
	ds_read_b128 v[216:219], v37 offset:20480
	ds_read_b128 v[220:223], v37 offset:21504
	ds_read_b128 v[224:227], v37 offset:22528
	ds_read_b128 v[228:231], v37 offset:23552
	global_load_lds_dwordx4 v[0:1], off
	s_mov_b32 m0, s46
	s_nop 0
	global_load_lds_dwordx4 v[2:3], off
	s_mov_b32 m0, s94
	s_nop 0
	global_load_lds_dwordx4 v[10:11], off
	s_mov_b32 m0, s87
	s_nop 0
	global_load_lds_dwordx4 v[12:13], off
	s_mov_b32 m0, s62
	s_nop 0
	global_load_lds_dwordx4 v[14:15], off
	s_mov_b32 m0, s8
	s_nop 0
	global_load_lds_dwordx4 v[24:25], off
	s_waitcnt vmcnt(8)
	s_waitcnt lgkmcnt(0)
	s_barrier
	s_waitcnt lgkmcnt(0)
	v_mfma_f32_16x16x32_bf16 v[0:3], v[148:151], v[78:81], v[32:35]
	v_mfma_f32_16x16x32_bf16 v[8:11], v[160:163], v[78:81], v[176:179]
	v_mfma_f32_16x16x32_bf16 v[12:15], v[148:151], v[118:121], v[180:183]
	v_mfma_f32_16x16x32_bf16 v[24:27], v[160:163], v[118:121], v[184:187]
	v_mfma_f32_16x16x32_bf16 v[32:35], v[148:151], v[216:219], v[188:191]
	v_mfma_f32_16x16x32_bf16 v[38:41], v[148:151], v[224:227], v[38:41]
	v_mfma_f32_16x16x32_bf16 v[0:3], v[156:159], v[114:117], v[0:3]
	v_mfma_f32_16x16x32_bf16 v[8:11], v[164:167], v[114:117], v[8:11]
	v_mfma_f32_16x16x32_bf16 v[12:15], v[156:159], v[122:125], v[12:15]
	v_mfma_f32_16x16x32_bf16 v[24:27], v[164:167], v[122:125], v[24:27]
	v_mfma_f32_16x16x32_bf16 v[32:35], v[156:159], v[220:223], v[32:35]
	v_mfma_f32_16x16x32_bf16 v[176:179], v[160:163], v[216:219], v[192:195]
	v_mfma_f32_16x16x32_bf16 v[148:151], v[156:159], v[228:231], v[38:41]
	v_mfma_f32_16x16x32_bf16 v[38:41], v[160:163], v[224:227], v[42:45]
	v_mfma_f32_16x16x32_bf16 v[176:179], v[164:167], v[220:223], v[176:179]
	v_mfma_f32_16x16x32_bf16 v[156:159], v[164:167], v[228:231], v[38:41]
	v_mfma_f32_16x16x32_bf16 v[38:41], v[168:171], v[78:81], v[46:49]
	v_mfma_f32_16x16x32_bf16 v[44:47], v[172:175], v[114:117], v[38:41]
	v_mfma_f32_16x16x32_bf16 v[38:41], v[196:199], v[78:81], v[50:53]
	v_mfma_f32_16x16x32_bf16 v[160:163], v[200:203], v[114:117], v[38:41]
	v_mfma_f32_16x16x32_bf16 v[38:41], v[168:171], v[118:121], v[62:65]
	v_mfma_f32_16x16x32_bf16 v[164:167], v[172:175], v[122:125], v[38:41]
	v_mfma_f32_16x16x32_bf16 v[38:41], v[196:199], v[118:121], v[66:69]
	v_mfma_f32_16x16x32_bf16 v[180:183], v[200:203], v[122:125], v[38:41]
	v_mfma_f32_16x16x32_bf16 v[38:41], v[168:171], v[216:219], v[98:101]
	v_mfma_f32_16x16x32_bf16 v[184:187], v[172:175], v[220:223], v[38:41]
	v_mfma_f32_16x16x32_bf16 v[38:41], v[196:199], v[216:219], v[138:141]
	v_mfma_f32_16x16x32_bf16 v[188:191], v[200:203], v[220:223], v[38:41]
	v_mfma_f32_16x16x32_bf16 v[38:41], v[168:171], v[224:227], v[54:57]
	v_mfma_f32_16x16x32_bf16 v[168:171], v[172:175], v[228:231], v[38:41]
	v_mfma_f32_16x16x32_bf16 v[38:41], v[196:199], v[224:227], v[58:61]
	v_mfma_f32_16x16x32_bf16 v[172:175], v[200:203], v[228:231], v[38:41]
	s_barrier
	ds_read_b128 v[52:55], v147
	ds_read_b128 v[56:59], v147 offset:1024
	ds_read_b128 v[192:195], v147 offset:2048
	ds_read_b128 v[196:199], v147 offset:3072
	ds_read_b128 v[200:203], v152
	ds_read_b128 v[216:219], v152 offset:1024
	ds_read_b128 v[220:223], v152 offset:2048
	ds_read_b128 v[224:227], v152 offset:3072
	s_mov_b32 m0, vcc_lo
	ds_read_b128 v[38:41], v37 offset:32768
	ds_read_b128 v[48:51], v37 offset:33792
	ds_read_b128 v[60:63], v37 offset:34816
	ds_read_b128 v[96:99], v37 offset:35840
	ds_read_b128 v[228:231], v37 offset:36864
	ds_read_b128 v[232:235], v37 offset:37888
	ds_read_b128 v[236:239], v37 offset:38912
	ds_read_b128 v[152:155], v37 offset:39936
	global_load_lds_dwordx4 v[4:5], off
	s_mov_b32 m0, vcc_hi
	s_nop 0
	global_load_lds_dwordx4 v[6:7], off
	s_waitcnt vmcnt(8)
	s_waitcnt lgkmcnt(0)
	s_barrier
	s_waitcnt lgkmcnt(0)
	v_mfma_f32_16x16x32_bf16 v[4:7], v[52:55], v[38:41], v[102:105]
	v_mfma_f32_16x16x32_bf16 v[120:123], v[56:59], v[48:51], v[4:7]
	v_mfma_f32_16x16x32_bf16 v[4:7], v[192:195], v[38:41], v[106:109]
	v_mfma_f32_16x16x32_bf16 v[124:127], v[196:199], v[48:51], v[4:7]
	v_mfma_f32_16x16x32_bf16 v[4:7], v[52:55], v[60:63], v[110:113]
	v_mfma_f32_16x16x32_bf16 v[112:115], v[56:59], v[96:99], v[4:7]
	v_mfma_f32_16x16x32_bf16 v[4:7], v[192:195], v[60:63], v[240:243]
	v_mfma_f32_16x16x32_bf16 v[116:119], v[196:199], v[96:99], v[4:7]
	v_mfma_f32_16x16x32_bf16 v[4:7], v[52:55], v[228:231], v[244:247]
	v_mfma_f32_16x16x32_bf16 v[108:111], v[56:59], v[232:235], v[4:7]
	v_mfma_f32_16x16x32_bf16 v[4:7], v[192:195], v[228:231], v[248:251]
	v_mfma_f32_16x16x32_bf16 v[104:107], v[196:199], v[232:235], v[4:7]
	v_mfma_f32_16x16x32_bf16 v[4:7], v[52:55], v[236:239], v[212:215]
	v_mfma_f32_16x16x32_bf16 v[80:83], v[56:59], v[152:155], v[4:7]
	v_mfma_f32_16x16x32_bf16 v[4:7], v[192:195], v[236:239], v[128:131]
	v_mfma_f32_16x16x32_bf16 v[64:67], v[196:199], v[152:155], v[4:7]
	v_mfma_f32_16x16x32_bf16 v[4:7], v[200:203], v[38:41], v[132:135]
	v_mfma_f32_16x16x32_bf16 v[136:139], v[216:219], v[48:51], v[4:7]
	v_mfma_f32_16x16x32_bf16 v[4:7], v[220:223], v[38:41], v[70:73]
	v_mfma_f32_16x16x32_bf16 v[140:143], v[224:227], v[48:51], v[4:7]
	v_mfma_f32_16x16x32_bf16 v[4:7], v[200:203], v[60:63], v[74:77]
	v_mfma_f32_16x16x32_bf16 v[128:131], v[216:219], v[96:99], v[4:7]
	v_mfma_f32_16x16x32_bf16 v[4:7], v[220:223], v[60:63], v[204:207]
	v_mfma_f32_16x16x32_bf16 v[132:135], v[224:227], v[96:99], v[4:7]
	v_mfma_f32_16x16x32_bf16 v[4:7], v[200:203], v[228:231], v[208:211]
	v_mfma_f32_16x16x32_bf16 v[100:103], v[216:219], v[232:235], v[4:7]
	v_mfma_f32_16x16x32_bf16 v[4:7], v[220:223], v[228:231], v[84:87]
	v_mfma_f32_16x16x32_bf16 v[96:99], v[224:227], v[232:235], v[4:7]
	v_mfma_f32_16x16x32_bf16 v[4:7], v[200:203], v[236:239], v[88:91]
	v_mfma_f32_16x16x32_bf16 v[84:87], v[216:219], v[152:155], v[4:7]
	v_mfma_f32_16x16x32_bf16 v[4:7], v[220:223], v[236:239], v[92:95]
	v_mfma_f32_16x16x32_bf16 v[68:71], v[224:227], v[152:155], v[4:7]
	s_barrier
	s_mov_b32 m0, s77
	s_nop 3
	ds_read_b128 v[4:7], v37 offset:49152
	ds_read_b128 v[76:79], v37 offset:50176
	ds_read_b128 v[152:155], v37 offset:51200
	ds_read_b128 v[204:207], v37 offset:52224
	ds_read_b128 v[208:211], v37 offset:53248
	ds_read_b128 v[212:215], v37 offset:54272
	ds_read_b128 v[228:231], v37 offset:55296
	ds_read_b128 v[232:235], v37 offset:56320
	global_load_lds_dwordx4 v[18:19], off
	s_mov_b32 m0, s0
	s_nop 0
	global_load_lds_dwordx4 v[20:21], off
	s_mov_b32 m0, s14
	s_nop 0
	global_load_lds_dwordx4 v[28:29], off
	s_mov_b32 m0, s15
	s_nop 0
	global_load_lds_dwordx4 v[30:31], off
	s_mov_b32 m0, s78
	s_nop 0
	global_load_lds_dwordx4 v[16:17], off
	s_mov_b32 m0, s1
	s_nop 0
	global_load_lds_dwordx4 v[22:23], off
	s_waitcnt vmcnt(8)
	s_waitcnt lgkmcnt(0)
	s_barrier
	s_waitcnt lgkmcnt(0)
	v_mfma_f32_16x16x32_bf16 v[0:3], v[52:55], v[4:7], v[0:3]
	v_mfma_f32_16x16x32_bf16 v[92:95], v[56:59], v[76:79], v[0:3]
	v_mfma_f32_16x16x32_bf16 v[0:3], v[192:195], v[4:7], v[8:11]
	v_mfma_f32_16x16x32_bf16 v[72:75], v[196:199], v[76:79], v[0:3]
	v_mfma_f32_16x16x32_bf16 v[0:3], v[52:55], v[152:155], v[12:15]
	v_mfma_f32_16x16x32_bf16 v[60:63], v[56:59], v[204:207], v[0:3]
	v_mfma_f32_16x16x32_bf16 v[0:3], v[192:195], v[152:155], v[24:27]
	v_mfma_f32_16x16x32_bf16 v[48:51], v[196:199], v[204:207], v[0:3]
	v_mfma_f32_16x16x32_bf16 v[0:3], v[52:55], v[208:211], v[32:35]
	v_mfma_f32_16x16x32_bf16 v[40:43], v[56:59], v[212:215], v[0:3]
	v_mfma_f32_16x16x32_bf16 v[0:3], v[192:195], v[208:211], v[176:179]
	v_mfma_f32_16x16x32_bf16 v[20:23], v[196:199], v[212:215], v[0:3]
	v_mfma_f32_16x16x32_bf16 v[0:3], v[52:55], v[228:231], v[148:151]
	v_mfma_f32_16x16x32_bf16 v[12:15], v[56:59], v[232:235], v[0:3]
	v_mfma_f32_16x16x32_bf16 v[0:3], v[192:195], v[228:231], v[156:159]
	v_mfma_f32_16x16x32_bf16 v[0:3], v[196:199], v[232:235], v[0:3]
	v_mfma_f32_16x16x32_bf16 v[8:11], v[200:203], v[4:7], v[44:47]
	v_mfma_f32_16x16x32_bf16 v[4:7], v[220:223], v[4:7], v[160:163]
	v_mfma_f32_16x16x32_bf16 v[88:91], v[216:219], v[76:79], v[8:11]
	v_mfma_f32_16x16x32_bf16 v[76:79], v[224:227], v[76:79], v[4:7]
	v_mfma_f32_16x16x32_bf16 v[4:7], v[200:203], v[152:155], v[164:167]
	v_mfma_f32_16x16x32_bf16 v[56:59], v[216:219], v[204:207], v[4:7]
	v_mfma_f32_16x16x32_bf16 v[4:7], v[220:223], v[152:155], v[180:183]
	v_mfma_f32_16x16x32_bf16 v[52:55], v[224:227], v[204:207], v[4:7]
	v_mfma_f32_16x16x32_bf16 v[4:7], v[200:203], v[208:211], v[184:187]
	v_mfma_f32_16x16x32_bf16 v[32:35], v[216:219], v[212:215], v[4:7]
	v_mfma_f32_16x16x32_bf16 v[4:7], v[220:223], v[208:211], v[188:191]
	v_mfma_f32_16x16x32_bf16 v[24:27], v[224:227], v[212:215], v[4:7]
	v_mfma_f32_16x16x32_bf16 v[4:7], v[200:203], v[228:231], v[168:171]
	v_mfma_f32_16x16x32_bf16 v[8:11], v[216:219], v[232:235], v[4:7]
	v_mfma_f32_16x16x32_bf16 v[4:7], v[220:223], v[228:231], v[172:175]
	v_mfma_f32_16x16x32_bf16 v[4:7], v[224:227], v[232:235], v[4:7]
	s_barrier
	s_cbranch_scc1 .LBB0_448
	s_barrier
	s_branch .LBB0_448

.LBB0_688:
	ds_read_b128 v[128:131], v165
	ds_read_b128 v[132:135], v165 offset:1024
	ds_read_b128 v[136:139], v165 offset:2048
	ds_read_b128 v[140:143], v165 offset:3072
	ds_read_b128 v[156:159], v166
	ds_read_b128 v[168:171], v166 offset:1024
	ds_read_b128 v[172:175], v166 offset:2048
	ds_read_b128 v[176:179], v166 offset:3072
	s_add_u32 s0, s74, 0xfff80080
	s_addc_u32 s1, s75, -1
	s_cmp_eq_u32 s91, 28
	s_cselect_b32 s79, s67, s1
	s_cselect_b32 s78, s87, s0
	s_cselect_b32 s77, s65, s90
	s_cselect_b32 s76, s88, s89
	v_lshl_add_u64 v[160:161], s[74:75], 0, v[148:149]
	s_add_i32 m0, s17, 0xc000
	ds_read_b128 v[180:183], v167
	ds_read_b128 v[184:187], v167 offset:1024
	ds_read_b128 v[188:191], v167 offset:2048
	ds_read_b128 v[192:195], v167 offset:3072
	ds_read_b128 v[196:199], v167 offset:4096
	ds_read_b128 v[200:203], v167 offset:5120
	ds_read_b128 v[204:207], v167 offset:6144
	ds_read_b128 v[208:211], v167 offset:7168
	global_load_lds_dwordx4 v[160:161], off
	v_lshl_add_u64 v[160:161], s[74:75], 0, v[150:151]
	s_add_i32 m0, s17, 0xe000
	s_nop 0
	global_load_lds_dwordx4 v[160:161], off
	s_waitcnt vmcnt(8)
	s_waitcnt lgkmcnt(0)
	s_barrier
	s_waitcnt lgkmcnt(0)
	v_mfma_f32_16x16x32_bf16 v[124:127], v[128:131], v[180:183], v[124:127]
	v_mfma_f32_16x16x32_bf16 v[120:123], v[136:139], v[180:183], v[120:123]
	v_mfma_f32_16x16x32_bf16 v[116:119], v[128:131], v[188:191], v[116:119]
	v_mfma_f32_16x16x32_bf16 v[112:115], v[136:139], v[188:191], v[112:115]
	v_mfma_f32_16x16x32_bf16 v[108:111], v[128:131], v[196:199], v[108:111]
	v_mfma_f32_16x16x32_bf16 v[96:99], v[136:139], v[196:199], v[96:99]
	v_mfma_f32_16x16x32_bf16 v[80:83], v[128:131], v[204:207], v[80:83]
	v_mfma_f32_16x16x32_bf16 v[72:75], v[136:139], v[204:207], v[72:75]
	v_mfma_f32_16x16x32_bf16 v[124:127], v[132:135], v[184:187], v[124:127]
	v_mfma_f32_16x16x32_bf16 v[120:123], v[140:143], v[184:187], v[120:123]
	v_mfma_f32_16x16x32_bf16 v[116:119], v[132:135], v[192:195], v[116:119]
	v_mfma_f32_16x16x32_bf16 v[112:115], v[140:143], v[192:195], v[112:115]
	v_mfma_f32_16x16x32_bf16 v[108:111], v[132:135], v[200:203], v[108:111]
	v_mfma_f32_16x16x32_bf16 v[96:99], v[140:143], v[200:203], v[96:99]
	v_mfma_f32_16x16x32_bf16 v[80:83], v[132:135], v[208:211], v[80:83]
	v_mfma_f32_16x16x32_bf16 v[72:75], v[140:143], v[208:211], v[72:75]
	v_mfma_f32_16x16x32_bf16 v[104:107], v[156:159], v[180:183], v[104:107]
	v_mfma_f32_16x16x32_bf16 v[100:103], v[172:175], v[180:183], v[100:103]
	v_mfma_f32_16x16x32_bf16 v[92:95], v[156:159], v[188:191], v[92:95]
	v_mfma_f32_16x16x32_bf16 v[88:91], v[172:175], v[188:191], v[88:91]
	v_mfma_f32_16x16x32_bf16 v[84:87], v[156:159], v[196:199], v[84:87]
	v_mfma_f32_16x16x32_bf16 v[76:79], v[172:175], v[196:199], v[76:79]
	v_mfma_f32_16x16x32_bf16 v[68:71], v[156:159], v[204:207], v[68:71]
	v_mfma_f32_16x16x32_bf16 v[64:67], v[172:175], v[204:207], v[64:67]
	v_mfma_f32_16x16x32_bf16 v[104:107], v[168:171], v[184:187], v[104:107]
	v_mfma_f32_16x16x32_bf16 v[100:103], v[176:179], v[184:187], v[100:103]
	v_mfma_f32_16x16x32_bf16 v[92:95], v[168:171], v[192:195], v[92:95]
	v_mfma_f32_16x16x32_bf16 v[88:91], v[176:179], v[192:195], v[88:91]
	v_mfma_f32_16x16x32_bf16 v[84:87], v[168:171], v[200:203], v[84:87]
	v_mfma_f32_16x16x32_bf16 v[76:79], v[176:179], v[200:203], v[76:79]
	v_mfma_f32_16x16x32_bf16 v[68:71], v[168:171], v[208:211], v[68:71]
	v_mfma_f32_16x16x32_bf16 v[64:67], v[176:179], v[208:211], v[64:67]
	s_barrier
	s_add_i32 s0, s84, s16
	v_lshl_add_u64 v[160:161], s[76:77], 0, v[144:145]
	s_mov_b32 m0, s0
	ds_read_b128 v[180:183], v167 offset:16384
	ds_read_b128 v[184:187], v167 offset:17408
	ds_read_b128 v[188:191], v167 offset:18432
	ds_read_b128 v[192:195], v167 offset:19456
	ds_read_b128 v[196:199], v167 offset:20480
	ds_read_b128 v[200:203], v167 offset:21504
	ds_read_b128 v[204:207], v167 offset:22528
	ds_read_b128 v[208:211], v167 offset:23552
	global_load_lds_dwordx4 v[160:161], off
	s_add_i32 m0, s0, 0x2000
	s_add_u32 s0, s76, 0x80000
	v_lshl_add_u64 v[212:213], s[76:77], 0, v[146:147]
	s_addc_u32 s1, s77, 0
	s_add_i32 s14, s85, s16
	global_load_lds_dwordx4 v[212:213], off
	v_lshl_add_u64 v[214:215], s[0:1], 0, v[144:145]
	s_mov_b32 m0, s14
	v_lshl_add_u64 v[216:217], s[78:79], 0, v[146:147]
	global_load_lds_dwordx4 v[214:215], off
	v_lshl_add_u64 v[214:215], s[0:1], 0, v[146:147]
	s_add_i32 m0, s14, 0x2000
	s_nop 0
	global_load_lds_dwordx4 v[214:215], off
	v_lshl_add_u64 v[214:215], s[78:79], 0, v[144:145]
	s_mov_b32 m0, s17
	s_nop 0
	global_load_lds_dwordx4 v[214:215], off
	s_mov_b32 m0, s38
	s_nop 0
	global_load_lds_dwordx4 v[216:217], off
	s_waitcnt vmcnt(8)
	s_waitcnt lgkmcnt(0)
	s_barrier
	s_waitcnt lgkmcnt(0)
	v_mfma_f32_16x16x32_bf16 v[60:63], v[128:131], v[180:183], v[60:63]
	v_mfma_f32_16x16x32_bf16 v[56:59], v[136:139], v[180:183], v[56:59]
	v_mfma_f32_16x16x32_bf16 v[52:55], v[128:131], v[188:191], v[52:55]
	v_mfma_f32_16x16x32_bf16 v[48:51], v[136:139], v[188:191], v[48:51]
	v_mfma_f32_16x16x32_bf16 v[44:47], v[128:131], v[196:199], v[44:47]
	v_mfma_f32_16x16x32_bf16 v[32:35], v[136:139], v[196:199], v[32:35]
	v_mfma_f32_16x16x32_bf16 v[16:19], v[128:131], v[204:207], v[16:19]
	v_mfma_f32_16x16x32_bf16 v[8:11], v[136:139], v[204:207], v[8:11]
	v_mfma_f32_16x16x32_bf16 v[60:63], v[132:135], v[184:187], v[60:63]
	v_mfma_f32_16x16x32_bf16 v[56:59], v[140:143], v[184:187], v[56:59]
	v_mfma_f32_16x16x32_bf16 v[52:55], v[132:135], v[192:195], v[52:55]
	v_mfma_f32_16x16x32_bf16 v[48:51], v[140:143], v[192:195], v[48:51]
	v_mfma_f32_16x16x32_bf16 v[44:47], v[132:135], v[200:203], v[44:47]
	v_mfma_f32_16x16x32_bf16 v[32:35], v[140:143], v[200:203], v[32:35]
	v_mfma_f32_16x16x32_bf16 v[16:19], v[132:135], v[208:211], v[16:19]
	v_mfma_f32_16x16x32_bf16 v[8:11], v[140:143], v[208:211], v[8:11]
	v_mfma_f32_16x16x32_bf16 v[40:43], v[156:159], v[180:183], v[40:43]
	v_mfma_f32_16x16x32_bf16 v[36:39], v[172:175], v[180:183], v[36:39]
	v_mfma_f32_16x16x32_bf16 v[28:31], v[156:159], v[188:191], v[28:31]
	v_mfma_f32_16x16x32_bf16 v[24:27], v[172:175], v[188:191], v[24:27]
	v_mfma_f32_16x16x32_bf16 v[20:23], v[156:159], v[196:199], v[20:23]
	v_mfma_f32_16x16x32_bf16 v[12:15], v[172:175], v[196:199], v[12:15]
	v_mfma_f32_16x16x32_bf16 v[4:7], v[156:159], v[204:207], v[4:7]
	v_mfma_f32_16x16x32_bf16 v[0:3], v[172:175], v[204:207], v[0:3]
	v_mfma_f32_16x16x32_bf16 v[40:43], v[168:171], v[184:187], v[40:43]
	v_mfma_f32_16x16x32_bf16 v[36:39], v[176:179], v[184:187], v[36:39]
	v_mfma_f32_16x16x32_bf16 v[28:31], v[168:171], v[192:195], v[28:31]
	v_mfma_f32_16x16x32_bf16 v[24:27], v[176:179], v[192:195], v[24:27]
	v_mfma_f32_16x16x32_bf16 v[20:23], v[168:171], v[200:203], v[20:23]
	v_mfma_f32_16x16x32_bf16 v[12:15], v[176:179], v[200:203], v[12:15]
	v_mfma_f32_16x16x32_bf16 v[4:7], v[168:171], v[208:211], v[4:7]
	v_mfma_f32_16x16x32_bf16 v[0:3], v[176:179], v[208:211], v[0:3]
	s_barrier
	s_add_i32 s14, 0, 0x18000
	s_add_i32 s15, 0, 0x1c000
	v_add_u32_e32 v140, s14, v163
	v_add_u32_e32 v176, s15, v163
	ds_read_b128 v[128:131], v140
	ds_read_b128 v[132:135], v140 offset:1024
	ds_read_b128 v[136:139], v140 offset:2048
	ds_read_b128 v[140:143], v140 offset:3072
	ds_read_b128 v[156:159], v176
	ds_read_b128 v[168:171], v176 offset:1024
	ds_read_b128 v[172:175], v176 offset:2048
	ds_read_b128 v[176:179], v176 offset:3072
	s_add_u32 s0, s78, 0x80000
	s_addc_u32 s1, s79, 0
	s_mov_b32 m0, s39
	v_lshl_add_u64 v[218:219], s[0:1], 0, v[144:145]
	ds_read_b128 v[180:183], v167 offset:32768
	ds_read_b128 v[184:187], v167 offset:33792
	ds_read_b128 v[188:191], v167 offset:34816
	ds_read_b128 v[192:195], v167 offset:35840
	ds_read_b128 v[196:199], v167 offset:36864
	ds_read_b128 v[200:203], v167 offset:37888
	ds_read_b128 v[204:207], v167 offset:38912
	ds_read_b128 v[208:211], v167 offset:39936
	global_load_lds_dwordx4 v[218:219], off
	v_lshl_add_u64 v[218:219], s[0:1], 0, v[146:147]
	s_mov_b32 m0, s73
	s_nop 0
	global_load_lds_dwordx4 v[218:219], off
	s_waitcnt vmcnt(8)
	s_waitcnt lgkmcnt(0)
	s_barrier
	s_waitcnt lgkmcnt(0)
	v_mfma_f32_16x16x32_bf16 v[124:127], v[128:131], v[180:183], v[124:127]
	v_mfma_f32_16x16x32_bf16 v[120:123], v[136:139], v[180:183], v[120:123]
	v_mfma_f32_16x16x32_bf16 v[116:119], v[128:131], v[188:191], v[116:119]
	v_mfma_f32_16x16x32_bf16 v[112:115], v[136:139], v[188:191], v[112:115]
	v_mfma_f32_16x16x32_bf16 v[108:111], v[128:131], v[196:199], v[108:111]
	v_mfma_f32_16x16x32_bf16 v[96:99], v[136:139], v[196:199], v[96:99]
	v_mfma_f32_16x16x32_bf16 v[80:83], v[128:131], v[204:207], v[80:83]
	v_mfma_f32_16x16x32_bf16 v[72:75], v[136:139], v[204:207], v[72:75]
	v_mfma_f32_16x16x32_bf16 v[124:127], v[132:135], v[184:187], v[124:127]
	v_mfma_f32_16x16x32_bf16 v[120:123], v[140:143], v[184:187], v[120:123]
	v_mfma_f32_16x16x32_bf16 v[116:119], v[132:135], v[192:195], v[116:119]
	v_mfma_f32_16x16x32_bf16 v[112:115], v[140:143], v[192:195], v[112:115]
	v_mfma_f32_16x16x32_bf16 v[108:111], v[132:135], v[200:203], v[108:111]
	v_mfma_f32_16x16x32_bf16 v[96:99], v[140:143], v[200:203], v[96:99]
	v_mfma_f32_16x16x32_bf16 v[80:83], v[132:135], v[208:211], v[80:83]
	v_mfma_f32_16x16x32_bf16 v[72:75], v[140:143], v[208:211], v[72:75]
	v_mfma_f32_16x16x32_bf16 v[104:107], v[156:159], v[180:183], v[104:107]
	v_mfma_f32_16x16x32_bf16 v[100:103], v[172:175], v[180:183], v[100:103]
	v_mfma_f32_16x16x32_bf16 v[92:95], v[156:159], v[188:191], v[92:95]
	v_mfma_f32_16x16x32_bf16 v[88:91], v[172:175], v[188:191], v[88:91]
	v_mfma_f32_16x16x32_bf16 v[84:87], v[156:159], v[196:199], v[84:87]
	v_mfma_f32_16x16x32_bf16 v[76:79], v[172:175], v[196:199], v[76:79]
	v_mfma_f32_16x16x32_bf16 v[68:71], v[156:159], v[204:207], v[68:71]
	v_mfma_f32_16x16x32_bf16 v[64:67], v[172:175], v[204:207], v[64:67]
	v_mfma_f32_16x16x32_bf16 v[104:107], v[168:171], v[184:187], v[104:107]
	v_mfma_f32_16x16x32_bf16 v[100:103], v[176:179], v[184:187], v[100:103]
	v_mfma_f32_16x16x32_bf16 v[92:95], v[168:171], v[192:195], v[92:95]
	v_mfma_f32_16x16x32_bf16 v[88:91], v[176:179], v[192:195], v[88:91]
	v_mfma_f32_16x16x32_bf16 v[84:87], v[168:171], v[200:203], v[84:87]
	v_mfma_f32_16x16x32_bf16 v[76:79], v[176:179], v[200:203], v[76:79]
	v_mfma_f32_16x16x32_bf16 v[68:71], v[168:171], v[208:211], v[68:71]
	v_mfma_f32_16x16x32_bf16 v[64:67], v[176:179], v[208:211], v[64:67]
	s_barrier
	s_add_i32 s0, s14, s16
	v_lshl_add_u64 v[160:161], v[160:161], 0, s[52:53]
	s_mov_b32 m0, s0
	ds_read_b128 v[180:183], v167 offset:49152
	ds_read_b128 v[184:187], v167 offset:50176
	ds_read_b128 v[188:191], v167 offset:51200
	ds_read_b128 v[192:195], v167 offset:52224
	ds_read_b128 v[196:199], v167 offset:53248
	ds_read_b128 v[200:203], v167 offset:54272
	ds_read_b128 v[204:207], v167 offset:55296
	ds_read_b128 v[208:211], v167 offset:56320
	global_load_lds_dwordx4 v[160:161], off
	s_add_i32 m0, s0, 0x2000
	s_add_u32 s0, s76, 0x80080
	v_lshl_add_u64 v[160:161], v[212:213], 0, s[52:53]
	s_addc_u32 s1, s77, 0
	s_add_i32 s14, s15, s16
	global_load_lds_dwordx4 v[160:161], off
	v_lshl_add_u64 v[160:161], s[0:1], 0, v[144:145]
	s_mov_b32 m0, s14
	s_nop 0
	global_load_lds_dwordx4 v[160:161], off
	v_lshl_add_u64 v[160:161], s[0:1], 0, v[146:147]
	s_add_i32 m0, s14, 0x2000
	s_nop 0
	global_load_lds_dwordx4 v[160:161], off
	v_lshl_add_u64 v[160:161], v[214:215], 0, s[52:53]
	s_mov_b32 m0, s81
	s_nop 0
	global_load_lds_dwordx4 v[160:161], off
	v_lshl_add_u64 v[160:161], v[216:217], 0, s[52:53]
	s_mov_b32 m0, s82
	s_nop 0
	global_load_lds_dwordx4 v[160:161], off
	s_waitcnt vmcnt(8)
	s_waitcnt lgkmcnt(0)
	s_barrier
	s_waitcnt lgkmcnt(0)
	v_mfma_f32_16x16x32_bf16 v[60:63], v[128:131], v[180:183], v[60:63]
	v_mfma_f32_16x16x32_bf16 v[56:59], v[136:139], v[180:183], v[56:59]
	v_mfma_f32_16x16x32_bf16 v[52:55], v[128:131], v[188:191], v[52:55]
	v_mfma_f32_16x16x32_bf16 v[48:51], v[136:139], v[188:191], v[48:51]
	v_mfma_f32_16x16x32_bf16 v[44:47], v[128:131], v[196:199], v[44:47]
	v_mfma_f32_16x16x32_bf16 v[32:35], v[136:139], v[196:199], v[32:35]
	v_mfma_f32_16x16x32_bf16 v[16:19], v[128:131], v[204:207], v[16:19]
	v_mfma_f32_16x16x32_bf16 v[8:11], v[136:139], v[204:207], v[8:11]
	v_mfma_f32_16x16x32_bf16 v[60:63], v[132:135], v[184:187], v[60:63]
	v_mfma_f32_16x16x32_bf16 v[56:59], v[140:143], v[184:187], v[56:59]
	v_mfma_f32_16x16x32_bf16 v[52:55], v[132:135], v[192:195], v[52:55]
	v_mfma_f32_16x16x32_bf16 v[48:51], v[140:143], v[192:195], v[48:51]
	v_mfma_f32_16x16x32_bf16 v[44:47], v[132:135], v[200:203], v[44:47]
	v_mfma_f32_16x16x32_bf16 v[32:35], v[140:143], v[200:203], v[32:35]
	v_mfma_f32_16x16x32_bf16 v[16:19], v[132:135], v[208:211], v[16:19]
	v_mfma_f32_16x16x32_bf16 v[8:11], v[140:143], v[208:211], v[8:11]
	v_mfma_f32_16x16x32_bf16 v[40:43], v[156:159], v[180:183], v[40:43]
	v_mfma_f32_16x16x32_bf16 v[36:39], v[172:175], v[180:183], v[36:39]
	v_mfma_f32_16x16x32_bf16 v[28:31], v[156:159], v[188:191], v[28:31]
	v_mfma_f32_16x16x32_bf16 v[24:27], v[172:175], v[188:191], v[24:27]
	v_mfma_f32_16x16x32_bf16 v[20:23], v[156:159], v[196:199], v[20:23]
	v_mfma_f32_16x16x32_bf16 v[12:15], v[172:175], v[196:199], v[12:15]
	v_mfma_f32_16x16x32_bf16 v[4:7], v[156:159], v[204:207], v[4:7]
	v_mfma_f32_16x16x32_bf16 v[0:3], v[172:175], v[204:207], v[0:3]
	v_mfma_f32_16x16x32_bf16 v[40:43], v[168:171], v[184:187], v[40:43]
	v_mfma_f32_16x16x32_bf16 v[36:39], v[176:179], v[184:187], v[36:39]
	v_mfma_f32_16x16x32_bf16 v[28:31], v[168:171], v[192:195], v[28:31]
	v_mfma_f32_16x16x32_bf16 v[24:27], v[176:179], v[192:195], v[24:27]
	v_mfma_f32_16x16x32_bf16 v[20:23], v[168:171], v[200:203], v[20:23]
	v_mfma_f32_16x16x32_bf16 v[12:15], v[176:179], v[200:203], v[12:15]
	v_mfma_f32_16x16x32_bf16 v[4:7], v[168:171], v[208:211], v[4:7]
	v_mfma_f32_16x16x32_bf16 v[0:3], v[176:179], v[208:211], v[0:3]
	s_barrier
	s_add_i32 s91, s91, 2
	s_add_u32 s74, s74, 0x100
	s_addc_u32 s75, s75, 0
	s_add_u32 s89, s89, 0x100
	s_addc_u32 s90, s90, 0
	s_cmp_gt_u32 s91, 29
	s_cbranch_scc0 .LBB0_688
	s_and_b64 vcc, exec, s[56:57]
	s_cbranch_vccz .LBB0_691
	s_barrier

.LBB0_824:
	v_add_u32_e32 v147, s85, v145
	ds_read_b128 v[148:151], v147
	ds_read_b128 v[152:155], v147 offset:1024
	ds_read_b128 v[156:159], v147 offset:2048
	ds_read_b128 v[160:163], v147 offset:3072
	v_add_u32_e32 v147, s86, v145
	s_add_u32 s0, s68, s76
	ds_read_b128 v[164:167], v147
	ds_read_b128 v[168:171], v147 offset:1024
	ds_read_b128 v[172:175], v147 offset:2048
	ds_read_b128 v[176:179], v147 offset:3072
	s_addc_u32 s1, s69, s77
	s_add_u32 s0, s0, 0x100
	s_addc_u32 s1, s1, 0
	s_add_u32 s14, s71, s76
	s_addc_u32 s15, s88, s77
	s_cmpk_eq_i32 s76, 0xf00
	s_cselect_b32 s81, s67, s1
	s_cselect_b32 s80, s89, s0
	s_cselect_b32 s79, s65, s15
	s_cselect_b32 s78, s90, s14
	v_lshl_add_u64 v[216:217], v[140:141], 0, s[76:77]
	s_add_i32 m0, s39, 0xc000
	ds_read_b128 v[180:183], v146
	ds_read_b128 v[184:187], v146 offset:1024
	ds_read_b128 v[188:191], v146 offset:2048
	ds_read_b128 v[192:195], v146 offset:3072
	ds_read_b128 v[196:199], v146 offset:4096
	ds_read_b128 v[200:203], v146 offset:5120
	ds_read_b128 v[204:207], v146 offset:6144
	ds_read_b128 v[210:213], v146 offset:7168
	global_load_lds_dwordx4 v[216:217], off
	v_lshl_add_u64 v[216:217], v[142:143], 0, s[76:77]
	s_add_i32 m0, s39, 0xe000
	s_nop 0
	global_load_lds_dwordx4 v[216:217], off
	s_waitcnt vmcnt(8)
	s_waitcnt lgkmcnt(0)
	s_barrier
	s_waitcnt lgkmcnt(0)
	v_mfma_f32_16x16x32_bf16 v[124:127], v[148:151], v[180:183], v[124:127]
	v_mfma_f32_16x16x32_bf16 v[120:123], v[156:159], v[180:183], v[120:123]
	v_mfma_f32_16x16x32_bf16 v[112:115], v[148:151], v[188:191], v[112:115]
	v_mfma_f32_16x16x32_bf16 v[104:107], v[156:159], v[188:191], v[104:107]
	v_mfma_f32_16x16x32_bf16 v[100:103], v[148:151], v[196:199], v[100:103]
	v_mfma_f32_16x16x32_bf16 v[92:95], v[156:159], v[196:199], v[92:95]
	v_mfma_f32_16x16x32_bf16 v[84:87], v[148:151], v[204:207], v[84:87]
	v_mfma_f32_16x16x32_bf16 v[76:79], v[156:159], v[204:207], v[76:79]
	v_mfma_f32_16x16x32_bf16 v[124:127], v[152:155], v[184:187], v[124:127]
	v_mfma_f32_16x16x32_bf16 v[120:123], v[160:163], v[184:187], v[120:123]
	v_mfma_f32_16x16x32_bf16 v[112:115], v[152:155], v[192:195], v[112:115]
	v_mfma_f32_16x16x32_bf16 v[104:107], v[160:163], v[192:195], v[104:107]
	v_mfma_f32_16x16x32_bf16 v[100:103], v[152:155], v[200:203], v[100:103]
	v_mfma_f32_16x16x32_bf16 v[92:95], v[160:163], v[200:203], v[92:95]
	v_mfma_f32_16x16x32_bf16 v[84:87], v[152:155], v[210:213], v[84:87]
	v_mfma_f32_16x16x32_bf16 v[76:79], v[160:163], v[210:213], v[76:79]
	v_mfma_f32_16x16x32_bf16 v[116:119], v[164:167], v[180:183], v[116:119]
	v_mfma_f32_16x16x32_bf16 v[108:111], v[172:175], v[180:183], v[108:111]
	v_mfma_f32_16x16x32_bf16 v[96:99], v[164:167], v[188:191], v[96:99]
	v_mfma_f32_16x16x32_bf16 v[88:91], v[172:175], v[188:191], v[88:91]
	v_mfma_f32_16x16x32_bf16 v[80:83], v[164:167], v[196:199], v[80:83]
	v_mfma_f32_16x16x32_bf16 v[72:75], v[172:175], v[196:199], v[72:75]
	v_mfma_f32_16x16x32_bf16 v[68:71], v[164:167], v[204:207], v[68:71]
	v_mfma_f32_16x16x32_bf16 v[64:67], v[172:175], v[204:207], v[64:67]
	v_mfma_f32_16x16x32_bf16 v[116:119], v[168:171], v[184:187], v[116:119]
	v_mfma_f32_16x16x32_bf16 v[108:111], v[176:179], v[184:187], v[108:111]
	v_mfma_f32_16x16x32_bf16 v[96:99], v[168:171], v[192:195], v[96:99]
	v_mfma_f32_16x16x32_bf16 v[88:91], v[176:179], v[192:195], v[88:91]
	v_mfma_f32_16x16x32_bf16 v[80:83], v[168:171], v[200:203], v[80:83]
	v_mfma_f32_16x16x32_bf16 v[72:75], v[176:179], v[200:203], v[72:75]
	v_mfma_f32_16x16x32_bf16 v[68:71], v[168:171], v[210:213], v[68:71]
	v_mfma_f32_16x16x32_bf16 v[64:67], v[176:179], v[210:213], v[64:67]
	s_barrier
	s_add_i32 s0, s85, s47
	v_lshl_add_u64 v[216:217], s[78:79], 0, v[130:131]
	s_mov_b32 m0, s0
	ds_read_b128 v[180:183], v146 offset:16384
	ds_read_b128 v[184:187], v146 offset:17408
	ds_read_b128 v[188:191], v146 offset:18432
	ds_read_b128 v[192:195], v146 offset:19456
	ds_read_b128 v[196:199], v146 offset:20480
	ds_read_b128 v[200:203], v146 offset:21504
	ds_read_b128 v[204:207], v146 offset:22528
	ds_read_b128 v[210:213], v146 offset:23552
	global_load_lds_dwordx4 v[216:217], off
	s_add_i32 m0, s0, 0x2000
	s_add_u32 s0, s78, 0x80000
	v_lshl_add_u64 v[218:219], s[78:79], 0, v[128:129]
	s_addc_u32 s1, s79, 0
	s_add_i32 s14, s86, s47
	global_load_lds_dwordx4 v[218:219], off
	v_lshl_add_u64 v[220:221], s[0:1], 0, v[130:131]
	s_mov_b32 m0, s14
	v_lshl_add_u64 v[222:223], s[80:81], 0, v[128:129]
	global_load_lds_dwordx4 v[220:221], off
	v_lshl_add_u64 v[220:221], s[0:1], 0, v[128:129]
	s_add_i32 m0, s14, 0x2000
	s_nop 0
	global_load_lds_dwordx4 v[220:221], off
	v_lshl_add_u64 v[220:221], s[80:81], 0, v[130:131]
	s_mov_b32 m0, s39
	s_nop 0
	global_load_lds_dwordx4 v[220:221], off
	s_mov_b32 m0, s48
	s_nop 0
	global_load_lds_dwordx4 v[222:223], off
	s_waitcnt vmcnt(8)
	s_waitcnt lgkmcnt(0)
	s_barrier
	s_waitcnt lgkmcnt(0)
	v_mfma_f32_16x16x32_bf16 v[60:63], v[148:151], v[180:183], v[60:63]
	v_mfma_f32_16x16x32_bf16 v[56:59], v[156:159], v[180:183], v[56:59]
	v_mfma_f32_16x16x32_bf16 v[48:51], v[148:151], v[188:191], v[48:51]
	v_mfma_f32_16x16x32_bf16 v[40:43], v[156:159], v[188:191], v[40:43]
	v_mfma_f32_16x16x32_bf16 v[36:39], v[148:151], v[196:199], v[36:39]
	v_mfma_f32_16x16x32_bf16 v[28:31], v[156:159], v[196:199], v[28:31]
	v_mfma_f32_16x16x32_bf16 v[20:23], v[148:151], v[204:207], v[20:23]
	v_mfma_f32_16x16x32_bf16 v[12:15], v[156:159], v[204:207], v[12:15]
	v_mfma_f32_16x16x32_bf16 v[60:63], v[152:155], v[184:187], v[60:63]
	v_mfma_f32_16x16x32_bf16 v[56:59], v[160:163], v[184:187], v[56:59]
	v_mfma_f32_16x16x32_bf16 v[48:51], v[152:155], v[192:195], v[48:51]
	v_mfma_f32_16x16x32_bf16 v[40:43], v[160:163], v[192:195], v[40:43]
	v_mfma_f32_16x16x32_bf16 v[36:39], v[152:155], v[200:203], v[36:39]
	v_mfma_f32_16x16x32_bf16 v[28:31], v[160:163], v[200:203], v[28:31]
	v_mfma_f32_16x16x32_bf16 v[20:23], v[152:155], v[210:213], v[20:23]
	v_mfma_f32_16x16x32_bf16 v[12:15], v[160:163], v[210:213], v[12:15]
	v_mfma_f32_16x16x32_bf16 v[52:55], v[164:167], v[180:183], v[52:55]
	v_mfma_f32_16x16x32_bf16 v[44:47], v[172:175], v[180:183], v[44:47]
	v_mfma_f32_16x16x32_bf16 v[32:35], v[164:167], v[188:191], v[32:35]
	v_mfma_f32_16x16x32_bf16 v[24:27], v[172:175], v[188:191], v[24:27]
	v_mfma_f32_16x16x32_bf16 v[16:19], v[164:167], v[196:199], v[16:19]
	v_mfma_f32_16x16x32_bf16 v[8:11], v[172:175], v[196:199], v[8:11]
	v_mfma_f32_16x16x32_bf16 v[4:7], v[164:167], v[204:207], v[4:7]
	v_mfma_f32_16x16x32_bf16 v[0:3], v[172:175], v[204:207], v[0:3]
	v_mfma_f32_16x16x32_bf16 v[52:55], v[168:171], v[184:187], v[52:55]
	v_mfma_f32_16x16x32_bf16 v[44:47], v[176:179], v[184:187], v[44:47]
	v_mfma_f32_16x16x32_bf16 v[32:35], v[168:171], v[192:195], v[32:35]
	v_mfma_f32_16x16x32_bf16 v[24:27], v[176:179], v[192:195], v[24:27]
	v_mfma_f32_16x16x32_bf16 v[16:19], v[168:171], v[200:203], v[16:19]
	v_mfma_f32_16x16x32_bf16 v[8:11], v[176:179], v[200:203], v[8:11]
	v_mfma_f32_16x16x32_bf16 v[4:7], v[168:171], v[210:213], v[4:7]
	v_mfma_f32_16x16x32_bf16 v[0:3], v[176:179], v[210:213], v[0:3]
	s_barrier
	s_add_i32 s14, 0, 0x18000
	v_add_u32_e32 v147, s14, v145
	s_add_i32 s15, 0, 0x1c000
	ds_read_b128 v[148:151], v147
	ds_read_b128 v[152:155], v147 offset:1024
	ds_read_b128 v[156:159], v147 offset:2048
	ds_read_b128 v[160:163], v147 offset:3072
	v_add_u32_e32 v147, s15, v145
	ds_read_b128 v[164:167], v147
	ds_read_b128 v[168:171], v147 offset:1024
	ds_read_b128 v[172:175], v147 offset:2048
	ds_read_b128 v[176:179], v147 offset:3072
	s_add_u32 s0, s80, 0x80000
	s_addc_u32 s1, s81, 0
	s_mov_b32 m0, s51
	v_lshl_add_u64 v[224:225], s[0:1], 0, v[130:131]
	ds_read_b128 v[180:183], v146 offset:32768
	ds_read_b128 v[184:187], v146 offset:33792
	ds_read_b128 v[188:191], v146 offset:34816
	ds_read_b128 v[192:195], v146 offset:35840
	ds_read_b128 v[196:199], v146 offset:36864
	ds_read_b128 v[200:203], v146 offset:37888
	ds_read_b128 v[204:207], v146 offset:38912
	ds_read_b128 v[210:213], v146 offset:39936
	global_load_lds_dwordx4 v[224:225], off
	v_lshl_add_u64 v[224:225], s[0:1], 0, v[128:129]
	s_mov_b32 m0, s53
	s_nop 0
	global_load_lds_dwordx4 v[224:225], off
	s_waitcnt vmcnt(8)
	s_waitcnt lgkmcnt(0)
	s_barrier
	s_waitcnt lgkmcnt(0)
	v_mfma_f32_16x16x32_bf16 v[124:127], v[148:151], v[180:183], v[124:127]
	v_mfma_f32_16x16x32_bf16 v[120:123], v[156:159], v[180:183], v[120:123]
	v_mfma_f32_16x16x32_bf16 v[112:115], v[148:151], v[188:191], v[112:115]
	v_mfma_f32_16x16x32_bf16 v[104:107], v[156:159], v[188:191], v[104:107]
	v_mfma_f32_16x16x32_bf16 v[100:103], v[148:151], v[196:199], v[100:103]
	v_mfma_f32_16x16x32_bf16 v[92:95], v[156:159], v[196:199], v[92:95]
	v_mfma_f32_16x16x32_bf16 v[84:87], v[148:151], v[204:207], v[84:87]
	v_mfma_f32_16x16x32_bf16 v[76:79], v[156:159], v[204:207], v[76:79]
	v_mfma_f32_16x16x32_bf16 v[124:127], v[152:155], v[184:187], v[124:127]
	v_mfma_f32_16x16x32_bf16 v[120:123], v[160:163], v[184:187], v[120:123]
	v_mfma_f32_16x16x32_bf16 v[112:115], v[152:155], v[192:195], v[112:115]
	v_mfma_f32_16x16x32_bf16 v[104:107], v[160:163], v[192:195], v[104:107]
	v_mfma_f32_16x16x32_bf16 v[100:103], v[152:155], v[200:203], v[100:103]
	v_mfma_f32_16x16x32_bf16 v[92:95], v[160:163], v[200:203], v[92:95]
	v_mfma_f32_16x16x32_bf16 v[84:87], v[152:155], v[210:213], v[84:87]
	v_mfma_f32_16x16x32_bf16 v[76:79], v[160:163], v[210:213], v[76:79]
	v_mfma_f32_16x16x32_bf16 v[116:119], v[164:167], v[180:183], v[116:119]
	v_mfma_f32_16x16x32_bf16 v[108:111], v[172:175], v[180:183], v[108:111]
	v_mfma_f32_16x16x32_bf16 v[96:99], v[164:167], v[188:191], v[96:99]
	v_mfma_f32_16x16x32_bf16 v[88:91], v[172:175], v[188:191], v[88:91]
	v_mfma_f32_16x16x32_bf16 v[80:83], v[164:167], v[196:199], v[80:83]
	v_mfma_f32_16x16x32_bf16 v[72:75], v[172:175], v[196:199], v[72:75]
	v_mfma_f32_16x16x32_bf16 v[68:71], v[164:167], v[204:207], v[68:71]
	v_mfma_f32_16x16x32_bf16 v[64:67], v[172:175], v[204:207], v[64:67]
	v_mfma_f32_16x16x32_bf16 v[116:119], v[168:171], v[184:187], v[116:119]
	v_mfma_f32_16x16x32_bf16 v[108:111], v[176:179], v[184:187], v[108:111]
	v_mfma_f32_16x16x32_bf16 v[96:99], v[168:171], v[192:195], v[96:99]
	v_mfma_f32_16x16x32_bf16 v[88:91], v[176:179], v[192:195], v[88:91]
	v_mfma_f32_16x16x32_bf16 v[80:83], v[168:171], v[200:203], v[80:83]
	v_mfma_f32_16x16x32_bf16 v[72:75], v[176:179], v[200:203], v[72:75]
	v_mfma_f32_16x16x32_bf16 v[68:71], v[168:171], v[210:213], v[68:71]
	v_mfma_f32_16x16x32_bf16 v[64:67], v[176:179], v[210:213], v[64:67]
	s_barrier
	s_add_i32 s0, s14, s47
	v_lshl_add_u64 v[216:217], v[216:217], 0, s[60:61]
	s_mov_b32 m0, s0
	ds_read_b128 v[180:183], v146 offset:49152
	ds_read_b128 v[184:187], v146 offset:50176
	ds_read_b128 v[188:191], v146 offset:51200
	ds_read_b128 v[192:195], v146 offset:52224
	ds_read_b128 v[196:199], v146 offset:53248
	ds_read_b128 v[200:203], v146 offset:54272
	ds_read_b128 v[204:207], v146 offset:55296
	ds_read_b128 v[210:213], v146 offset:56320
	global_load_lds_dwordx4 v[216:217], off
	s_add_i32 m0, s0, 0x2000
	s_add_u32 s0, s78, 0x80080
	v_lshl_add_u64 v[216:217], v[218:219], 0, s[60:61]
	s_addc_u32 s1, s79, 0
	s_add_i32 s14, s15, s47
	global_load_lds_dwordx4 v[216:217], off
	v_lshl_add_u64 v[216:217], s[0:1], 0, v[130:131]
	s_mov_b32 m0, s14
	s_nop 0
	global_load_lds_dwordx4 v[216:217], off
	v_lshl_add_u64 v[216:217], s[0:1], 0, v[128:129]
	s_add_i32 m0, s14, 0x2000
	s_nop 0
	global_load_lds_dwordx4 v[216:217], off
	v_lshl_add_u64 v[216:217], v[220:221], 0, s[60:61]
	s_mov_b32 m0, s56
	s_nop 0
	global_load_lds_dwordx4 v[216:217], off
	v_lshl_add_u64 v[216:217], v[222:223], 0, s[60:61]
	s_mov_b32 m0, s84
	s_nop 0
	global_load_lds_dwordx4 v[216:217], off
	s_waitcnt vmcnt(8)
	s_waitcnt lgkmcnt(0)
	s_barrier
	s_waitcnt lgkmcnt(0)
	v_mfma_f32_16x16x32_bf16 v[60:63], v[148:151], v[180:183], v[60:63]
	v_mfma_f32_16x16x32_bf16 v[56:59], v[156:159], v[180:183], v[56:59]
	v_mfma_f32_16x16x32_bf16 v[48:51], v[148:151], v[188:191], v[48:51]
	v_mfma_f32_16x16x32_bf16 v[40:43], v[156:159], v[188:191], v[40:43]
	v_mfma_f32_16x16x32_bf16 v[36:39], v[148:151], v[196:199], v[36:39]
	v_mfma_f32_16x16x32_bf16 v[28:31], v[156:159], v[196:199], v[28:31]
	v_mfma_f32_16x16x32_bf16 v[20:23], v[148:151], v[204:207], v[20:23]
	v_mfma_f32_16x16x32_bf16 v[12:15], v[156:159], v[204:207], v[12:15]
	v_mfma_f32_16x16x32_bf16 v[60:63], v[152:155], v[184:187], v[60:63]
	v_mfma_f32_16x16x32_bf16 v[56:59], v[160:163], v[184:187], v[56:59]
	v_mfma_f32_16x16x32_bf16 v[48:51], v[152:155], v[192:195], v[48:51]
	v_mfma_f32_16x16x32_bf16 v[40:43], v[160:163], v[192:195], v[40:43]
	v_mfma_f32_16x16x32_bf16 v[36:39], v[152:155], v[200:203], v[36:39]
	v_mfma_f32_16x16x32_bf16 v[28:31], v[160:163], v[200:203], v[28:31]
	v_mfma_f32_16x16x32_bf16 v[20:23], v[152:155], v[210:213], v[20:23]
	v_mfma_f32_16x16x32_bf16 v[12:15], v[160:163], v[210:213], v[12:15]
	v_mfma_f32_16x16x32_bf16 v[52:55], v[164:167], v[180:183], v[52:55]
	v_mfma_f32_16x16x32_bf16 v[44:47], v[172:175], v[180:183], v[44:47]
	v_mfma_f32_16x16x32_bf16 v[32:35], v[164:167], v[188:191], v[32:35]
	v_mfma_f32_16x16x32_bf16 v[24:27], v[172:175], v[188:191], v[24:27]
	v_mfma_f32_16x16x32_bf16 v[16:19], v[164:167], v[196:199], v[16:19]
	v_mfma_f32_16x16x32_bf16 v[8:11], v[172:175], v[196:199], v[8:11]
	v_mfma_f32_16x16x32_bf16 v[4:7], v[164:167], v[204:207], v[4:7]
	v_mfma_f32_16x16x32_bf16 v[0:3], v[172:175], v[204:207], v[0:3]
	v_mfma_f32_16x16x32_bf16 v[52:55], v[168:171], v[184:187], v[52:55]
	v_mfma_f32_16x16x32_bf16 v[44:47], v[176:179], v[184:187], v[44:47]
	v_mfma_f32_16x16x32_bf16 v[32:35], v[168:171], v[192:195], v[32:35]
	v_mfma_f32_16x16x32_bf16 v[24:27], v[176:179], v[192:195], v[24:27]
	v_mfma_f32_16x16x32_bf16 v[16:19], v[168:171], v[200:203], v[16:19]
	v_mfma_f32_16x16x32_bf16 v[8:11], v[176:179], v[200:203], v[8:11]
	v_mfma_f32_16x16x32_bf16 v[4:7], v[168:171], v[210:213], v[4:7]
	v_mfma_f32_16x16x32_bf16 v[0:3], v[176:179], v[210:213], v[0:3]
	s_barrier
	s_add_i32 s91, s91, 2
	s_add_u32 s76, s76, 0x100
	s_addc_u32 s77, s77, 0
	s_cmp_gt_u32 s91, 29
	s_cbranch_scc0 .LBB0_824
	s_and_b64 vcc, exec, s[62:63]
	s_cbranch_vccz .LBB0_827
	s_barrier

.LBB0_927:
	ds_read_b128 v[146:149], v142
	ds_read_b128 v[150:153], v142 offset:1024
	ds_read_b128 v[154:157], v142 offset:2048
	ds_read_b128 v[158:161], v142 offset:3072
	ds_read_b128 v[162:165], v143
	ds_read_b128 v[166:169], v143 offset:1024
	ds_read_b128 v[170:173], v143 offset:2048
	ds_read_b128 v[174:177], v143 offset:3072
	s_add_u32 s0, s60, 0xfff80080
	s_addc_u32 s1, s61, -1
	s_cmp_eq_u32 s77, 28
	s_cselect_b32 s65, s51, s1
	s_cselect_b32 s64, s73, s0
	s_cselect_b32 s63, s49, s76
	s_cselect_b32 s62, s74, s75
	v_lshl_add_u64 v[210:211], s[60:61], 0, v[134:135]
	s_add_i32 m0, s16, 0xc000
	ds_read_b128 v[178:181], v144
	ds_read_b128 v[182:185], v144 offset:1024
	ds_read_b128 v[186:189], v144 offset:2048
	ds_read_b128 v[190:193], v144 offset:3072
	ds_read_b128 v[194:197], v144 offset:4096
	ds_read_b128 v[198:201], v144 offset:5120
	ds_read_b128 v[202:205], v144 offset:6144
	ds_read_b128 v[206:209], v144 offset:7168
	global_load_lds_dwordx4 v[210:211], off
	v_lshl_add_u64 v[210:211], s[60:61], 0, v[136:137]
	s_add_i32 m0, s16, 0xe000
	s_nop 0
	global_load_lds_dwordx4 v[210:211], off
	s_waitcnt vmcnt(8)
	s_waitcnt lgkmcnt(0)
	s_barrier
	s_waitcnt lgkmcnt(0)
	v_mfma_f32_16x16x32_bf16 v[124:127], v[146:149], v[178:181], v[124:127]
	v_mfma_f32_16x16x32_bf16 v[120:123], v[154:157], v[178:181], v[120:123]
	v_mfma_f32_16x16x32_bf16 v[108:111], v[146:149], v[186:189], v[108:111]
	v_mfma_f32_16x16x32_bf16 v[104:107], v[154:157], v[186:189], v[104:107]
	v_mfma_f32_16x16x32_bf16 v[92:95], v[146:149], v[194:197], v[92:95]
	v_mfma_f32_16x16x32_bf16 v[88:91], v[154:157], v[194:197], v[88:91]
	v_mfma_f32_16x16x32_bf16 v[76:79], v[146:149], v[202:205], v[76:79]
	v_mfma_f32_16x16x32_bf16 v[72:75], v[154:157], v[202:205], v[72:75]
	v_mfma_f32_16x16x32_bf16 v[124:127], v[150:153], v[182:185], v[124:127]
	v_mfma_f32_16x16x32_bf16 v[120:123], v[158:161], v[182:185], v[120:123]
	v_mfma_f32_16x16x32_bf16 v[108:111], v[150:153], v[190:193], v[108:111]
	v_mfma_f32_16x16x32_bf16 v[104:107], v[158:161], v[190:193], v[104:107]
	v_mfma_f32_16x16x32_bf16 v[92:95], v[150:153], v[198:201], v[92:95]
	v_mfma_f32_16x16x32_bf16 v[88:91], v[158:161], v[198:201], v[88:91]
	v_mfma_f32_16x16x32_bf16 v[76:79], v[150:153], v[206:209], v[76:79]
	v_mfma_f32_16x16x32_bf16 v[72:75], v[158:161], v[206:209], v[72:75]
	v_mfma_f32_16x16x32_bf16 v[116:119], v[162:165], v[178:181], v[116:119]
	v_mfma_f32_16x16x32_bf16 v[112:115], v[170:173], v[178:181], v[112:115]
	v_mfma_f32_16x16x32_bf16 v[100:103], v[162:165], v[186:189], v[100:103]
	v_mfma_f32_16x16x32_bf16 v[96:99], v[170:173], v[186:189], v[96:99]
	v_mfma_f32_16x16x32_bf16 v[84:87], v[162:165], v[194:197], v[84:87]
	v_mfma_f32_16x16x32_bf16 v[80:83], v[170:173], v[194:197], v[80:83]
	v_mfma_f32_16x16x32_bf16 v[68:71], v[162:165], v[202:205], v[68:71]
	v_mfma_f32_16x16x32_bf16 v[64:67], v[170:173], v[202:205], v[64:67]
	v_mfma_f32_16x16x32_bf16 v[116:119], v[166:169], v[182:185], v[116:119]
	v_mfma_f32_16x16x32_bf16 v[112:115], v[174:177], v[182:185], v[112:115]
	v_mfma_f32_16x16x32_bf16 v[100:103], v[166:169], v[190:193], v[100:103]
	v_mfma_f32_16x16x32_bf16 v[96:99], v[174:177], v[190:193], v[96:99]
	v_mfma_f32_16x16x32_bf16 v[84:87], v[166:169], v[198:201], v[84:87]
	v_mfma_f32_16x16x32_bf16 v[80:83], v[174:177], v[198:201], v[80:83]
	v_mfma_f32_16x16x32_bf16 v[68:71], v[166:169], v[206:209], v[68:71]
	v_mfma_f32_16x16x32_bf16 v[64:67], v[174:177], v[206:209], v[64:67]
	s_barrier
	s_add_i32 s0, s47, s8
	v_lshl_add_u64 v[210:211], s[62:63], 0, v[130:131]
	s_mov_b32 m0, s0
	ds_read_b128 v[178:181], v144 offset:16384
	ds_read_b128 v[182:185], v144 offset:17408
	ds_read_b128 v[186:189], v144 offset:18432
	ds_read_b128 v[190:193], v144 offset:19456
	ds_read_b128 v[194:197], v144 offset:20480
	ds_read_b128 v[198:201], v144 offset:21504
	ds_read_b128 v[202:205], v144 offset:22528
	ds_read_b128 v[206:209], v144 offset:23552
	global_load_lds_dwordx4 v[210:211], off
	s_add_i32 m0, s0, 0x2000
	s_add_u32 s0, s62, 0x80000
	v_lshl_add_u64 v[212:213], s[62:63], 0, v[128:129]
	s_addc_u32 s1, s63, 0
	s_add_i32 s14, s71, s8
	global_load_lds_dwordx4 v[212:213], off
	v_lshl_add_u64 v[214:215], s[0:1], 0, v[130:131]
	s_mov_b32 m0, s14
	v_lshl_add_u64 v[216:217], s[64:65], 0, v[128:129]
	global_load_lds_dwordx4 v[214:215], off
	v_lshl_add_u64 v[214:215], s[0:1], 0, v[128:129]
	s_add_i32 m0, s14, 0x2000
	s_nop 0
	global_load_lds_dwordx4 v[214:215], off
	v_lshl_add_u64 v[214:215], s[64:65], 0, v[130:131]
	s_mov_b32 m0, s16
	s_nop 0
	global_load_lds_dwordx4 v[214:215], off
	s_mov_b32 m0, s17
	s_nop 0
	global_load_lds_dwordx4 v[216:217], off
	s_waitcnt vmcnt(8)
	s_waitcnt lgkmcnt(0)
	s_barrier
	s_waitcnt lgkmcnt(0)
	v_mfma_f32_16x16x32_bf16 v[60:63], v[146:149], v[178:181], v[60:63]
	v_mfma_f32_16x16x32_bf16 v[56:59], v[154:157], v[178:181], v[56:59]
	v_mfma_f32_16x16x32_bf16 v[44:47], v[146:149], v[186:189], v[44:47]
	v_mfma_f32_16x16x32_bf16 v[40:43], v[154:157], v[186:189], v[40:43]
	v_mfma_f32_16x16x32_bf16 v[28:31], v[146:149], v[194:197], v[28:31]
	v_mfma_f32_16x16x32_bf16 v[24:27], v[154:157], v[194:197], v[24:27]
	v_mfma_f32_16x16x32_bf16 v[12:15], v[146:149], v[202:205], v[12:15]
	v_mfma_f32_16x16x32_bf16 v[8:11], v[154:157], v[202:205], v[8:11]
	v_mfma_f32_16x16x32_bf16 v[60:63], v[150:153], v[182:185], v[60:63]
	v_mfma_f32_16x16x32_bf16 v[56:59], v[158:161], v[182:185], v[56:59]
	v_mfma_f32_16x16x32_bf16 v[44:47], v[150:153], v[190:193], v[44:47]
	v_mfma_f32_16x16x32_bf16 v[40:43], v[158:161], v[190:193], v[40:43]
	v_mfma_f32_16x16x32_bf16 v[28:31], v[150:153], v[198:201], v[28:31]
	v_mfma_f32_16x16x32_bf16 v[24:27], v[158:161], v[198:201], v[24:27]
	v_mfma_f32_16x16x32_bf16 v[12:15], v[150:153], v[206:209], v[12:15]
	v_mfma_f32_16x16x32_bf16 v[8:11], v[158:161], v[206:209], v[8:11]
	v_mfma_f32_16x16x32_bf16 v[52:55], v[162:165], v[178:181], v[52:55]
	v_mfma_f32_16x16x32_bf16 v[48:51], v[170:173], v[178:181], v[48:51]
	v_mfma_f32_16x16x32_bf16 v[36:39], v[162:165], v[186:189], v[36:39]
	v_mfma_f32_16x16x32_bf16 v[32:35], v[170:173], v[186:189], v[32:35]
	v_mfma_f32_16x16x32_bf16 v[20:23], v[162:165], v[194:197], v[20:23]
	v_mfma_f32_16x16x32_bf16 v[16:19], v[170:173], v[194:197], v[16:19]
	v_mfma_f32_16x16x32_bf16 v[4:7], v[162:165], v[202:205], v[4:7]
	v_mfma_f32_16x16x32_bf16 v[0:3], v[170:173], v[202:205], v[0:3]
	v_mfma_f32_16x16x32_bf16 v[52:55], v[166:169], v[182:185], v[52:55]
	v_mfma_f32_16x16x32_bf16 v[48:51], v[174:177], v[182:185], v[48:51]
	v_mfma_f32_16x16x32_bf16 v[36:39], v[166:169], v[190:193], v[36:39]
	v_mfma_f32_16x16x32_bf16 v[32:35], v[174:177], v[190:193], v[32:35]
	v_mfma_f32_16x16x32_bf16 v[20:23], v[166:169], v[198:201], v[20:23]
	v_mfma_f32_16x16x32_bf16 v[16:19], v[174:177], v[198:201], v[16:19]
	v_mfma_f32_16x16x32_bf16 v[4:7], v[166:169], v[206:209], v[4:7]
	v_mfma_f32_16x16x32_bf16 v[0:3], v[174:177], v[206:209], v[0:3]
	s_barrier
	s_add_i32 s14, 0, 0x18000
	v_add_u32_e32 v145, s14, v141
	s_add_i32 s15, 0, 0x1c000
	ds_read_b128 v[146:149], v145
	ds_read_b128 v[150:153], v145 offset:1024
	ds_read_b128 v[154:157], v145 offset:2048
	ds_read_b128 v[158:161], v145 offset:3072
	v_add_u32_e32 v145, s15, v141
	ds_read_b128 v[162:165], v145
	ds_read_b128 v[166:169], v145 offset:1024
	ds_read_b128 v[170:173], v145 offset:2048
	ds_read_b128 v[174:177], v145 offset:3072
	s_add_u32 s0, s64, 0x80000
	s_addc_u32 s1, s65, 0
	s_mov_b32 m0, s35
	v_lshl_add_u64 v[218:219], s[0:1], 0, v[130:131]
	ds_read_b128 v[178:181], v144 offset:32768
	ds_read_b128 v[182:185], v144 offset:33792
	ds_read_b128 v[186:189], v144 offset:34816
	ds_read_b128 v[190:193], v144 offset:35840
	ds_read_b128 v[194:197], v144 offset:36864
	ds_read_b128 v[198:201], v144 offset:37888
	ds_read_b128 v[202:205], v144 offset:38912
	ds_read_b128 v[206:209], v144 offset:39936
	global_load_lds_dwordx4 v[218:219], off
	v_lshl_add_u64 v[218:219], s[0:1], 0, v[128:129]
	s_mov_b32 m0, s66
	s_nop 0
	global_load_lds_dwordx4 v[218:219], off
	s_waitcnt vmcnt(8)
	s_waitcnt lgkmcnt(0)
	s_barrier
	s_waitcnt lgkmcnt(0)
	v_mfma_f32_16x16x32_bf16 v[124:127], v[146:149], v[178:181], v[124:127]
	v_mfma_f32_16x16x32_bf16 v[120:123], v[154:157], v[178:181], v[120:123]
	v_mfma_f32_16x16x32_bf16 v[108:111], v[146:149], v[186:189], v[108:111]
	v_mfma_f32_16x16x32_bf16 v[104:107], v[154:157], v[186:189], v[104:107]
	v_mfma_f32_16x16x32_bf16 v[92:95], v[146:149], v[194:197], v[92:95]
	v_mfma_f32_16x16x32_bf16 v[88:91], v[154:157], v[194:197], v[88:91]
	v_mfma_f32_16x16x32_bf16 v[76:79], v[146:149], v[202:205], v[76:79]
	v_mfma_f32_16x16x32_bf16 v[72:75], v[154:157], v[202:205], v[72:75]
	v_mfma_f32_16x16x32_bf16 v[124:127], v[150:153], v[182:185], v[124:127]
	v_mfma_f32_16x16x32_bf16 v[120:123], v[158:161], v[182:185], v[120:123]
	v_mfma_f32_16x16x32_bf16 v[108:111], v[150:153], v[190:193], v[108:111]
	v_mfma_f32_16x16x32_bf16 v[104:107], v[158:161], v[190:193], v[104:107]
	v_mfma_f32_16x16x32_bf16 v[92:95], v[150:153], v[198:201], v[92:95]
	v_mfma_f32_16x16x32_bf16 v[88:91], v[158:161], v[198:201], v[88:91]
	v_mfma_f32_16x16x32_bf16 v[76:79], v[150:153], v[206:209], v[76:79]
	v_mfma_f32_16x16x32_bf16 v[72:75], v[158:161], v[206:209], v[72:75]
	v_mfma_f32_16x16x32_bf16 v[116:119], v[162:165], v[178:181], v[116:119]
	v_mfma_f32_16x16x32_bf16 v[112:115], v[170:173], v[178:181], v[112:115]
	v_mfma_f32_16x16x32_bf16 v[100:103], v[162:165], v[186:189], v[100:103]
	v_mfma_f32_16x16x32_bf16 v[96:99], v[170:173], v[186:189], v[96:99]
	v_mfma_f32_16x16x32_bf16 v[84:87], v[162:165], v[194:197], v[84:87]
	v_mfma_f32_16x16x32_bf16 v[80:83], v[170:173], v[194:197], v[80:83]
	v_mfma_f32_16x16x32_bf16 v[68:71], v[162:165], v[202:205], v[68:71]
	v_mfma_f32_16x16x32_bf16 v[64:67], v[170:173], v[202:205], v[64:67]
	v_mfma_f32_16x16x32_bf16 v[116:119], v[166:169], v[182:185], v[116:119]
	v_mfma_f32_16x16x32_bf16 v[112:115], v[174:177], v[182:185], v[112:115]
	v_mfma_f32_16x16x32_bf16 v[100:103], v[166:169], v[190:193], v[100:103]
	v_mfma_f32_16x16x32_bf16 v[96:99], v[174:177], v[190:193], v[96:99]
	v_mfma_f32_16x16x32_bf16 v[84:87], v[166:169], v[198:201], v[84:87]
	v_mfma_f32_16x16x32_bf16 v[80:83], v[174:177], v[198:201], v[80:83]
	v_mfma_f32_16x16x32_bf16 v[68:71], v[166:169], v[206:209], v[68:71]
	v_mfma_f32_16x16x32_bf16 v[64:67], v[174:177], v[206:209], v[64:67]
	s_barrier
	s_add_i32 s0, s14, s8
	v_lshl_add_u64 v[210:211], v[210:211], 0, s[38:39]
	s_mov_b32 m0, s0
	ds_read_b128 v[178:181], v144 offset:49152
	ds_read_b128 v[182:185], v144 offset:50176
	ds_read_b128 v[186:189], v144 offset:51200
	ds_read_b128 v[190:193], v144 offset:52224
	ds_read_b128 v[194:197], v144 offset:53248
	ds_read_b128 v[198:201], v144 offset:54272
	ds_read_b128 v[202:205], v144 offset:55296
	ds_read_b128 v[206:209], v144 offset:56320
	global_load_lds_dwordx4 v[210:211], off
	s_add_i32 m0, s0, 0x2000
	s_add_u32 s0, s62, 0x80080
	v_lshl_add_u64 v[210:211], v[212:213], 0, s[38:39]
	s_addc_u32 s1, s63, 0
	s_add_i32 s14, s15, s8
	global_load_lds_dwordx4 v[210:211], off
	v_lshl_add_u64 v[210:211], s[0:1], 0, v[130:131]
	s_mov_b32 m0, s14
	s_nop 0
	global_load_lds_dwordx4 v[210:211], off
	v_lshl_add_u64 v[210:211], s[0:1], 0, v[128:129]
	s_add_i32 m0, s14, 0x2000
	s_nop 0
	global_load_lds_dwordx4 v[210:211], off
	v_lshl_add_u64 v[210:211], v[214:215], 0, s[38:39]
	s_mov_b32 m0, s67
	s_nop 0
	global_load_lds_dwordx4 v[210:211], off
	v_lshl_add_u64 v[210:211], v[216:217], 0, s[38:39]
	s_mov_b32 m0, s68
	s_nop 0
	global_load_lds_dwordx4 v[210:211], off
	s_waitcnt vmcnt(8)
	s_waitcnt lgkmcnt(0)
	s_barrier
	s_waitcnt lgkmcnt(0)
	v_mfma_f32_16x16x32_bf16 v[60:63], v[146:149], v[178:181], v[60:63]
	v_mfma_f32_16x16x32_bf16 v[56:59], v[154:157], v[178:181], v[56:59]
	v_mfma_f32_16x16x32_bf16 v[44:47], v[146:149], v[186:189], v[44:47]
	v_mfma_f32_16x16x32_bf16 v[40:43], v[154:157], v[186:189], v[40:43]
	v_mfma_f32_16x16x32_bf16 v[28:31], v[146:149], v[194:197], v[28:31]
	v_mfma_f32_16x16x32_bf16 v[24:27], v[154:157], v[194:197], v[24:27]
	v_mfma_f32_16x16x32_bf16 v[12:15], v[146:149], v[202:205], v[12:15]
	v_mfma_f32_16x16x32_bf16 v[8:11], v[154:157], v[202:205], v[8:11]
	v_mfma_f32_16x16x32_bf16 v[60:63], v[150:153], v[182:185], v[60:63]
	v_mfma_f32_16x16x32_bf16 v[56:59], v[158:161], v[182:185], v[56:59]
	v_mfma_f32_16x16x32_bf16 v[44:47], v[150:153], v[190:193], v[44:47]
	v_mfma_f32_16x16x32_bf16 v[40:43], v[158:161], v[190:193], v[40:43]
	v_mfma_f32_16x16x32_bf16 v[28:31], v[150:153], v[198:201], v[28:31]
	v_mfma_f32_16x16x32_bf16 v[24:27], v[158:161], v[198:201], v[24:27]
	v_mfma_f32_16x16x32_bf16 v[12:15], v[150:153], v[206:209], v[12:15]
	v_mfma_f32_16x16x32_bf16 v[8:11], v[158:161], v[206:209], v[8:11]
	v_mfma_f32_16x16x32_bf16 v[52:55], v[162:165], v[178:181], v[52:55]
	v_mfma_f32_16x16x32_bf16 v[48:51], v[170:173], v[178:181], v[48:51]
	v_mfma_f32_16x16x32_bf16 v[36:39], v[162:165], v[186:189], v[36:39]
	v_mfma_f32_16x16x32_bf16 v[32:35], v[170:173], v[186:189], v[32:35]
	v_mfma_f32_16x16x32_bf16 v[20:23], v[162:165], v[194:197], v[20:23]
	v_mfma_f32_16x16x32_bf16 v[16:19], v[170:173], v[194:197], v[16:19]
	v_mfma_f32_16x16x32_bf16 v[4:7], v[162:165], v[202:205], v[4:7]
	v_mfma_f32_16x16x32_bf16 v[0:3], v[170:173], v[202:205], v[0:3]
	v_mfma_f32_16x16x32_bf16 v[52:55], v[166:169], v[182:185], v[52:55]
	v_mfma_f32_16x16x32_bf16 v[48:51], v[174:177], v[182:185], v[48:51]
	v_mfma_f32_16x16x32_bf16 v[36:39], v[166:169], v[190:193], v[36:39]
	v_mfma_f32_16x16x32_bf16 v[32:35], v[174:177], v[190:193], v[32:35]
	v_mfma_f32_16x16x32_bf16 v[20:23], v[166:169], v[198:201], v[20:23]
	v_mfma_f32_16x16x32_bf16 v[16:19], v[174:177], v[198:201], v[16:19]
	v_mfma_f32_16x16x32_bf16 v[4:7], v[166:169], v[206:209], v[4:7]
	v_mfma_f32_16x16x32_bf16 v[0:3], v[174:177], v[206:209], v[0:3]
	s_barrier
	s_add_i32 s77, s77, 2
	s_add_u32 s60, s60, 0x100
	s_addc_u32 s61, s61, 0
	s_add_u32 s75, s75, 0x100
	s_addc_u32 s76, s76, 0
	s_cmp_gt_u32 s77, 29
	s_cbranch_scc0 .LBB0_927
	s_and_b64 vcc, exec, s[42:43]
	s_cbranch_vccz .LBB0_930
	s_barrier

.LBB0_939:
	s_add_u32 s0, s48, s50
	ds_read_b128 v[78:81], v74
	ds_read_b128 v[82:85], v74 offset:1024
	ds_read_b128 v[86:89], v74 offset:2048
	ds_read_b128 v[90:93], v74 offset:3072
	s_addc_u32 s1, s49, s51
	s_add_u32 s0, s0, 0x6000100
	s_addc_u32 s1, s1, 0
	s_add_u32 s14, s63, s50
	s_addc_u32 s15, s64, s51
	s_cmpk_eq_i32 s50, 0xf00
	s_cselect_b32 s15, s45, s15
	s_cselect_b32 s14, s39, s14
	s_cselect_b32 s53, s5, s1
	s_cselect_b32 s52, s4, s0
	s_mov_b32 m0, s66
	v_lshl_add_u64 v[126:127], v[68:69], 0, s[50:51]
	ds_read_b128 v[94:97], v75
	ds_read_b128 v[98:101], v75 offset:1024
	ds_read_b128 v[102:105], v75 offset:2048
	ds_read_b128 v[106:109], v75 offset:3072
	ds_read_b128 v[110:113], v75 offset:4096
	ds_read_b128 v[114:117], v75 offset:5120
	ds_read_b128 v[118:121], v75 offset:6144
	ds_read_b128 v[122:125], v75 offset:7168
	global_load_lds_dwordx4 v[126:127], off
	v_lshl_add_u64 v[126:127], v[70:71], 0, s[50:51]
	s_mov_b32 m0, s67
	s_nop 0
	global_load_lds_dwordx4 v[126:127], off
	s_waitcnt vmcnt(6)
	s_waitcnt lgkmcnt(0)
	s_barrier
	s_waitcnt lgkmcnt(0)
	v_mfma_f32_16x16x32_bf16 v[60:63], v[78:81], v[94:97], v[60:63]
	v_mfma_f32_16x16x32_bf16 v[56:59], v[86:89], v[94:97], v[56:59]
	v_mfma_f32_16x16x32_bf16 v[52:55], v[78:81], v[102:105], v[52:55]
	v_mfma_f32_16x16x32_bf16 v[48:51], v[86:89], v[102:105], v[48:51]
	v_mfma_f32_16x16x32_bf16 v[44:47], v[78:81], v[110:113], v[44:47]
	v_mfma_f32_16x16x32_bf16 v[40:43], v[86:89], v[110:113], v[40:43]
	v_mfma_f32_16x16x32_bf16 v[36:39], v[78:81], v[118:121], v[36:39]
	v_mfma_f32_16x16x32_bf16 v[32:35], v[86:89], v[118:121], v[32:35]
	v_mfma_f32_16x16x32_bf16 v[60:63], v[82:85], v[98:101], v[60:63]
	v_mfma_f32_16x16x32_bf16 v[56:59], v[90:93], v[98:101], v[56:59]
	v_mfma_f32_16x16x32_bf16 v[52:55], v[82:85], v[106:109], v[52:55]
	v_mfma_f32_16x16x32_bf16 v[48:51], v[90:93], v[106:109], v[48:51]
	v_mfma_f32_16x16x32_bf16 v[44:47], v[82:85], v[114:117], v[44:47]
	v_mfma_f32_16x16x32_bf16 v[40:43], v[90:93], v[114:117], v[40:43]
	v_mfma_f32_16x16x32_bf16 v[36:39], v[82:85], v[122:125], v[36:39]
	v_mfma_f32_16x16x32_bf16 v[32:35], v[90:93], v[122:125], v[32:35]
	s_barrier
	s_add_u32 s0, s14, 0x80000
	s_addc_u32 s1, s15, 0
	s_mov_b32 m0, s68
	v_lshl_add_u64 v[126:127], s[0:1], 0, v[66:67]
	ds_read_b128 v[94:97], v75 offset:16384
	ds_read_b128 v[98:101], v75 offset:17408
	ds_read_b128 v[102:105], v75 offset:18432
	ds_read_b128 v[106:109], v75 offset:19456
	ds_read_b128 v[110:113], v75 offset:20480
	ds_read_b128 v[114:117], v75 offset:21504
	ds_read_b128 v[118:121], v75 offset:22528
	ds_read_b128 v[122:125], v75 offset:23552
	global_load_lds_dwordx4 v[126:127], off
	v_lshl_add_u64 v[126:127], s[0:1], 0, v[64:65]
	s_mov_b32 m0, s69
	v_lshl_add_u64 v[128:129], s[52:53], 0, v[64:65]
	global_load_lds_dwordx4 v[126:127], off
	v_lshl_add_u64 v[126:127], s[52:53], 0, v[66:67]
	s_mov_b32 m0, s56
	s_nop 0
	global_load_lds_dwordx4 v[126:127], off
	s_mov_b32 m0, s57
	s_nop 0
	global_load_lds_dwordx4 v[128:129], off
	s_waitcnt vmcnt(6)
	s_waitcnt lgkmcnt(0)
	s_barrier
	s_waitcnt lgkmcnt(0)
	v_mfma_f32_16x16x32_bf16 v[28:31], v[78:81], v[94:97], v[28:31]
	v_mfma_f32_16x16x32_bf16 v[24:27], v[86:89], v[94:97], v[24:27]
	v_mfma_f32_16x16x32_bf16 v[20:23], v[78:81], v[102:105], v[20:23]
	v_mfma_f32_16x16x32_bf16 v[16:19], v[86:89], v[102:105], v[16:19]
	v_mfma_f32_16x16x32_bf16 v[12:15], v[78:81], v[110:113], v[12:15]
	v_mfma_f32_16x16x32_bf16 v[8:11], v[86:89], v[110:113], v[8:11]
	v_mfma_f32_16x16x32_bf16 v[4:7], v[78:81], v[118:121], v[4:7]
	v_mfma_f32_16x16x32_bf16 v[0:3], v[86:89], v[118:121], v[0:3]
	v_mfma_f32_16x16x32_bf16 v[28:31], v[82:85], v[98:101], v[28:31]
	v_mfma_f32_16x16x32_bf16 v[24:27], v[90:93], v[98:101], v[24:27]
	v_mfma_f32_16x16x32_bf16 v[20:23], v[82:85], v[106:109], v[20:23]
	v_mfma_f32_16x16x32_bf16 v[16:19], v[90:93], v[106:109], v[16:19]
	v_mfma_f32_16x16x32_bf16 v[12:15], v[82:85], v[114:117], v[12:15]
	v_mfma_f32_16x16x32_bf16 v[8:11], v[90:93], v[114:117], v[8:11]
	v_mfma_f32_16x16x32_bf16 v[4:7], v[82:85], v[122:125], v[4:7]
	v_mfma_f32_16x16x32_bf16 v[0:3], v[90:93], v[122:125], v[0:3]
	s_barrier
	ds_read_b128 v[78:81], v76
	ds_read_b128 v[82:85], v76 offset:1024
	ds_read_b128 v[86:89], v76 offset:2048
	ds_read_b128 v[90:93], v76 offset:3072
	s_add_u32 s0, s52, 0x80000
	s_addc_u32 s1, s53, 0
	s_mov_b32 m0, s58
	v_lshl_add_u64 v[130:131], s[0:1], 0, v[66:67]
	ds_read_b128 v[94:97], v75 offset:32768
	ds_read_b128 v[98:101], v75 offset:33792
	ds_read_b128 v[102:105], v75 offset:34816
	ds_read_b128 v[106:109], v75 offset:35840
	ds_read_b128 v[110:113], v75 offset:36864
	ds_read_b128 v[114:117], v75 offset:37888
	ds_read_b128 v[118:121], v75 offset:38912
	ds_read_b128 v[122:125], v75 offset:39936
	global_load_lds_dwordx4 v[130:131], off
	v_lshl_add_u64 v[130:131], s[0:1], 0, v[64:65]
	s_mov_b32 m0, s59
	s_nop 0
	global_load_lds_dwordx4 v[130:131], off
	s_waitcnt vmcnt(6)
	s_waitcnt lgkmcnt(0)
	s_barrier
	s_waitcnt lgkmcnt(0)
	v_mfma_f32_16x16x32_bf16 v[60:63], v[78:81], v[94:97], v[60:63]
	v_mfma_f32_16x16x32_bf16 v[56:59], v[86:89], v[94:97], v[56:59]
	v_mfma_f32_16x16x32_bf16 v[52:55], v[78:81], v[102:105], v[52:55]
	v_mfma_f32_16x16x32_bf16 v[48:51], v[86:89], v[102:105], v[48:51]
	v_mfma_f32_16x16x32_bf16 v[44:47], v[78:81], v[110:113], v[44:47]
	v_mfma_f32_16x16x32_bf16 v[40:43], v[86:89], v[110:113], v[40:43]
	v_mfma_f32_16x16x32_bf16 v[36:39], v[78:81], v[118:121], v[36:39]
	v_mfma_f32_16x16x32_bf16 v[32:35], v[86:89], v[118:121], v[32:35]
	v_mfma_f32_16x16x32_bf16 v[60:63], v[82:85], v[98:101], v[60:63]
	v_mfma_f32_16x16x32_bf16 v[56:59], v[90:93], v[98:101], v[56:59]
	v_mfma_f32_16x16x32_bf16 v[52:55], v[82:85], v[106:109], v[52:55]
	v_mfma_f32_16x16x32_bf16 v[48:51], v[90:93], v[106:109], v[48:51]
	v_mfma_f32_16x16x32_bf16 v[44:47], v[82:85], v[114:117], v[44:47]
	v_mfma_f32_16x16x32_bf16 v[40:43], v[90:93], v[114:117], v[40:43]
	v_mfma_f32_16x16x32_bf16 v[36:39], v[82:85], v[122:125], v[36:39]
	v_mfma_f32_16x16x32_bf16 v[32:35], v[90:93], v[122:125], v[32:35]
	s_barrier
	s_add_u32 s0, s14, 0x80080
	s_addc_u32 s1, s15, 0
	s_mov_b32 m0, s70
	v_lshl_add_u64 v[130:131], s[0:1], 0, v[66:67]
	ds_read_b128 v[94:97], v75 offset:49152
	ds_read_b128 v[98:101], v75 offset:50176
	ds_read_b128 v[102:105], v75 offset:51200
	ds_read_b128 v[106:109], v75 offset:52224
	ds_read_b128 v[110:113], v75 offset:53248
	ds_read_b128 v[114:117], v75 offset:54272
	ds_read_b128 v[118:121], v75 offset:55296
	ds_read_b128 v[122:125], v75 offset:56320
	global_load_lds_dwordx4 v[130:131], off
	v_lshl_add_u64 v[130:131], s[0:1], 0, v[64:65]
	s_mov_b32 m0, s71
	v_lshl_add_u64 v[126:127], v[126:127], 0, s[6:7]
	global_load_lds_dwordx4 v[130:131], off
	s_mov_b32 m0, s61
	s_nop 0
	global_load_lds_dwordx4 v[126:127], off
	v_lshl_add_u64 v[126:127], v[128:129], 0, s[6:7]
	s_mov_b32 m0, s62
	s_nop 0
	global_load_lds_dwordx4 v[126:127], off
	s_waitcnt vmcnt(6)
	s_waitcnt lgkmcnt(0)
	s_barrier
	s_waitcnt lgkmcnt(0)
	v_mfma_f32_16x16x32_bf16 v[28:31], v[78:81], v[94:97], v[28:31]
	v_mfma_f32_16x16x32_bf16 v[24:27], v[86:89], v[94:97], v[24:27]
	v_mfma_f32_16x16x32_bf16 v[20:23], v[78:81], v[102:105], v[20:23]
	v_mfma_f32_16x16x32_bf16 v[16:19], v[86:89], v[102:105], v[16:19]
	v_mfma_f32_16x16x32_bf16 v[12:15], v[78:81], v[110:113], v[12:15]
	v_mfma_f32_16x16x32_bf16 v[8:11], v[86:89], v[110:113], v[8:11]
	v_mfma_f32_16x16x32_bf16 v[4:7], v[78:81], v[118:121], v[4:7]
	v_mfma_f32_16x16x32_bf16 v[0:3], v[86:89], v[118:121], v[0:3]
	v_mfma_f32_16x16x32_bf16 v[28:31], v[82:85], v[98:101], v[28:31]
	v_mfma_f32_16x16x32_bf16 v[24:27], v[90:93], v[98:101], v[24:27]
	v_mfma_f32_16x16x32_bf16 v[20:23], v[82:85], v[106:109], v[20:23]
	v_mfma_f32_16x16x32_bf16 v[16:19], v[90:93], v[106:109], v[16:19]
	v_mfma_f32_16x16x32_bf16 v[12:15], v[82:85], v[114:117], v[12:15]
	v_mfma_f32_16x16x32_bf16 v[8:11], v[90:93], v[114:117], v[8:11]
	v_mfma_f32_16x16x32_bf16 v[4:7], v[82:85], v[122:125], v[4:7]
	v_mfma_f32_16x16x32_bf16 v[0:3], v[90:93], v[122:125], v[0:3]
	s_barrier
	s_add_i32 s65, s65, 2
	s_add_u32 s50, s50, 0x100
	s_addc_u32 s51, s51, 0
	s_cmp_gt_u32 s65, 29
	s_cbranch_scc0 .LBB0_939
	s_cmpk_lt_u32 s47, 0x100
	s_cbranch_scc0 .LBB0_942
	s_barrier

.LBB0_979:
	s_add_u32 s14, s40, s46
	ds_read_b128 v[78:81], v74
	ds_read_b128 v[82:85], v74 offset:1024
	ds_read_b128 v[86:89], v74 offset:2048
	ds_read_b128 v[90:93], v74 offset:3072
	s_addc_u32 s15, s41, s47
	s_add_u32 s14, s14, 0x6000100
	s_addc_u32 s15, s15, 0
	s_add_u32 s60, s8, s46
	s_addc_u32 s61, s9, s47
	s_cmpk_eq_i32 s46, 0xf00
	s_cselect_b32 s49, s7, s15
	s_cselect_b32 s48, s6, s14
	s_cselect_b32 s15, s5, s61
	s_cselect_b32 s14, s4, s60
	s_mov_b32 m0, s17
	v_lshl_add_u64 v[126:127], v[68:69], 0, s[46:47]
	ds_read_b128 v[94:97], v75
	ds_read_b128 v[98:101], v75 offset:1024
	ds_read_b128 v[102:105], v75 offset:2048
	ds_read_b128 v[106:109], v75 offset:3072
	ds_read_b128 v[110:113], v75 offset:4096
	ds_read_b128 v[114:117], v75 offset:5120
	ds_read_b128 v[118:121], v75 offset:6144
	ds_read_b128 v[122:125], v75 offset:7168
	global_load_lds_dwordx4 v[126:127], off
	v_lshl_add_u64 v[126:127], v[70:71], 0, s[46:47]
	s_mov_b32 m0, s45
	s_nop 0
	global_load_lds_dwordx4 v[126:127], off
	s_waitcnt vmcnt(6)
	s_waitcnt lgkmcnt(0)
	s_barrier
	s_waitcnt lgkmcnt(0)
	v_mfma_f32_16x16x32_bf16 v[60:63], v[78:81], v[94:97], v[60:63]
	v_mfma_f32_16x16x32_bf16 v[56:59], v[86:89], v[94:97], v[56:59]
	v_mfma_f32_16x16x32_bf16 v[52:55], v[78:81], v[102:105], v[52:55]
	v_mfma_f32_16x16x32_bf16 v[48:51], v[86:89], v[102:105], v[48:51]
	v_mfma_f32_16x16x32_bf16 v[44:47], v[78:81], v[110:113], v[44:47]
	v_mfma_f32_16x16x32_bf16 v[40:43], v[86:89], v[110:113], v[40:43]
	v_mfma_f32_16x16x32_bf16 v[36:39], v[78:81], v[118:121], v[36:39]
	v_mfma_f32_16x16x32_bf16 v[32:35], v[86:89], v[118:121], v[32:35]
	v_mfma_f32_16x16x32_bf16 v[60:63], v[82:85], v[98:101], v[60:63]
	v_mfma_f32_16x16x32_bf16 v[56:59], v[90:93], v[98:101], v[56:59]
	v_mfma_f32_16x16x32_bf16 v[52:55], v[82:85], v[106:109], v[52:55]
	v_mfma_f32_16x16x32_bf16 v[48:51], v[90:93], v[106:109], v[48:51]
	v_mfma_f32_16x16x32_bf16 v[44:47], v[82:85], v[114:117], v[44:47]
	v_mfma_f32_16x16x32_bf16 v[40:43], v[90:93], v[114:117], v[40:43]
	v_mfma_f32_16x16x32_bf16 v[36:39], v[82:85], v[122:125], v[36:39]
	v_mfma_f32_16x16x32_bf16 v[32:35], v[90:93], v[122:125], v[32:35]
	s_barrier
	s_mov_b32 m0, s0
	v_lshl_add_u64 v[126:127], s[14:15], 0, v[66:67]
	ds_read_b128 v[94:97], v75 offset:16384
	ds_read_b128 v[98:101], v75 offset:17408
	ds_read_b128 v[102:105], v75 offset:18432
	ds_read_b128 v[106:109], v75 offset:19456
	ds_read_b128 v[110:113], v75 offset:20480
	ds_read_b128 v[114:117], v75 offset:21504
	ds_read_b128 v[118:121], v75 offset:22528
	ds_read_b128 v[122:125], v75 offset:23552
	global_load_lds_dwordx4 v[126:127], off
	v_lshl_add_u64 v[128:129], s[14:15], 0, v[64:65]
	s_mov_b32 m0, s1
	v_lshl_add_u64 v[130:131], s[48:49], 0, v[66:67]
	global_load_lds_dwordx4 v[128:129], off
	s_mov_b32 m0, s50
	v_lshl_add_u64 v[132:133], s[48:49], 0, v[64:65]
	global_load_lds_dwordx4 v[130:131], off
	s_mov_b32 m0, s51
	s_nop 0
	global_load_lds_dwordx4 v[132:133], off
	s_waitcnt vmcnt(6)
	s_waitcnt lgkmcnt(0)
	s_barrier
	s_waitcnt lgkmcnt(0)
	v_mfma_f32_16x16x32_bf16 v[28:31], v[78:81], v[94:97], v[28:31]
	v_mfma_f32_16x16x32_bf16 v[24:27], v[86:89], v[94:97], v[24:27]
	v_mfma_f32_16x16x32_bf16 v[20:23], v[78:81], v[102:105], v[20:23]
	v_mfma_f32_16x16x32_bf16 v[16:19], v[86:89], v[102:105], v[16:19]
	v_mfma_f32_16x16x32_bf16 v[12:15], v[78:81], v[110:113], v[12:15]
	v_mfma_f32_16x16x32_bf16 v[8:11], v[86:89], v[110:113], v[8:11]
	v_mfma_f32_16x16x32_bf16 v[4:7], v[78:81], v[118:121], v[4:7]
	v_mfma_f32_16x16x32_bf16 v[0:3], v[86:89], v[118:121], v[0:3]
	v_mfma_f32_16x16x32_bf16 v[28:31], v[82:85], v[98:101], v[28:31]
	v_mfma_f32_16x16x32_bf16 v[24:27], v[90:93], v[98:101], v[24:27]
	v_mfma_f32_16x16x32_bf16 v[20:23], v[82:85], v[106:109], v[20:23]
	v_mfma_f32_16x16x32_bf16 v[16:19], v[90:93], v[106:109], v[16:19]
	v_mfma_f32_16x16x32_bf16 v[12:15], v[82:85], v[114:117], v[12:15]
	v_mfma_f32_16x16x32_bf16 v[8:11], v[90:93], v[114:117], v[8:11]
	v_mfma_f32_16x16x32_bf16 v[4:7], v[82:85], v[122:125], v[4:7]
	v_mfma_f32_16x16x32_bf16 v[0:3], v[90:93], v[122:125], v[0:3]
	s_barrier
	ds_read_b128 v[78:81], v76
	ds_read_b128 v[82:85], v76 offset:1024
	ds_read_b128 v[86:89], v76 offset:2048
	ds_read_b128 v[90:93], v76 offset:3072
	s_add_u32 s14, s48, 0x80000
	s_addc_u32 s15, s49, 0
	s_mov_b32 m0, s52
	v_lshl_add_u64 v[134:135], s[14:15], 0, v[66:67]
	ds_read_b128 v[94:97], v75 offset:32768
	ds_read_b128 v[98:101], v75 offset:33792
	ds_read_b128 v[102:105], v75 offset:34816
	ds_read_b128 v[106:109], v75 offset:35840
	ds_read_b128 v[110:113], v75 offset:36864
	ds_read_b128 v[114:117], v75 offset:37888
	ds_read_b128 v[118:121], v75 offset:38912
	ds_read_b128 v[122:125], v75 offset:39936
	global_load_lds_dwordx4 v[134:135], off
	v_lshl_add_u64 v[134:135], s[14:15], 0, v[64:65]
	s_mov_b32 m0, s53
	s_nop 0
	global_load_lds_dwordx4 v[134:135], off
	s_waitcnt vmcnt(6)
	s_waitcnt lgkmcnt(0)
	s_barrier
	s_waitcnt lgkmcnt(0)
	v_mfma_f32_16x16x32_bf16 v[60:63], v[78:81], v[94:97], v[60:63]
	v_mfma_f32_16x16x32_bf16 v[56:59], v[86:89], v[94:97], v[56:59]
	v_mfma_f32_16x16x32_bf16 v[52:55], v[78:81], v[102:105], v[52:55]
	v_mfma_f32_16x16x32_bf16 v[48:51], v[86:89], v[102:105], v[48:51]
	v_mfma_f32_16x16x32_bf16 v[44:47], v[78:81], v[110:113], v[44:47]
	v_mfma_f32_16x16x32_bf16 v[40:43], v[86:89], v[110:113], v[40:43]
	v_mfma_f32_16x16x32_bf16 v[36:39], v[78:81], v[118:121], v[36:39]
	v_mfma_f32_16x16x32_bf16 v[32:35], v[86:89], v[118:121], v[32:35]
	v_mfma_f32_16x16x32_bf16 v[60:63], v[82:85], v[98:101], v[60:63]
	v_mfma_f32_16x16x32_bf16 v[56:59], v[90:93], v[98:101], v[56:59]
	v_mfma_f32_16x16x32_bf16 v[52:55], v[82:85], v[106:109], v[52:55]
	v_mfma_f32_16x16x32_bf16 v[48:51], v[90:93], v[106:109], v[48:51]
	v_mfma_f32_16x16x32_bf16 v[44:47], v[82:85], v[114:117], v[44:47]
	v_mfma_f32_16x16x32_bf16 v[40:43], v[90:93], v[114:117], v[40:43]
	v_mfma_f32_16x16x32_bf16 v[36:39], v[82:85], v[122:125], v[36:39]
	v_mfma_f32_16x16x32_bf16 v[32:35], v[90:93], v[122:125], v[32:35]
	s_barrier
	s_mov_b32 m0, s58
	v_lshl_add_u64 v[126:127], v[126:127], 0, s[26:27]
	ds_read_b128 v[94:97], v75 offset:49152
	ds_read_b128 v[98:101], v75 offset:50176
	ds_read_b128 v[102:105], v75 offset:51200
	ds_read_b128 v[106:109], v75 offset:52224
	ds_read_b128 v[110:113], v75 offset:53248
	ds_read_b128 v[114:117], v75 offset:54272
	ds_read_b128 v[118:121], v75 offset:55296
	ds_read_b128 v[122:125], v75 offset:56320
	global_load_lds_dwordx4 v[126:127], off
	v_lshl_add_u64 v[126:127], v[128:129], 0, s[26:27]
	s_mov_b32 m0, s59
	s_nop 0
	global_load_lds_dwordx4 v[126:127], off
	v_lshl_add_u64 v[126:127], v[130:131], 0, s[26:27]
	s_mov_b32 m0, s56
	s_nop 0
	global_load_lds_dwordx4 v[126:127], off
	v_lshl_add_u64 v[126:127], v[132:133], 0, s[26:27]
	s_mov_b32 m0, s57
	s_nop 0
	global_load_lds_dwordx4 v[126:127], off
	s_waitcnt vmcnt(6)
	s_waitcnt lgkmcnt(0)
	s_barrier
	s_waitcnt lgkmcnt(0)
	v_mfma_f32_16x16x32_bf16 v[28:31], v[78:81], v[94:97], v[28:31]
	v_mfma_f32_16x16x32_bf16 v[24:27], v[86:89], v[94:97], v[24:27]
	v_mfma_f32_16x16x32_bf16 v[20:23], v[78:81], v[102:105], v[20:23]
	v_mfma_f32_16x16x32_bf16 v[16:19], v[86:89], v[102:105], v[16:19]
	v_mfma_f32_16x16x32_bf16 v[12:15], v[78:81], v[110:113], v[12:15]
	v_mfma_f32_16x16x32_bf16 v[8:11], v[86:89], v[110:113], v[8:11]
	v_mfma_f32_16x16x32_bf16 v[4:7], v[78:81], v[118:121], v[4:7]
	v_mfma_f32_16x16x32_bf16 v[0:3], v[86:89], v[118:121], v[0:3]
	v_mfma_f32_16x16x32_bf16 v[28:31], v[82:85], v[98:101], v[28:31]
	v_mfma_f32_16x16x32_bf16 v[24:27], v[90:93], v[98:101], v[24:27]
	v_mfma_f32_16x16x32_bf16 v[20:23], v[82:85], v[106:109], v[20:23]
	v_mfma_f32_16x16x32_bf16 v[16:19], v[90:93], v[106:109], v[16:19]
	v_mfma_f32_16x16x32_bf16 v[12:15], v[82:85], v[114:117], v[12:15]
	v_mfma_f32_16x16x32_bf16 v[8:11], v[90:93], v[114:117], v[8:11]
	v_mfma_f32_16x16x32_bf16 v[4:7], v[82:85], v[122:125], v[4:7]
	v_mfma_f32_16x16x32_bf16 v[0:3], v[90:93], v[122:125], v[0:3]
	s_barrier
	s_add_i32 s16, s16, 2
	s_add_u32 s46, s46, 0x100
	s_addc_u32 s47, s47, 0
	s_cmp_gt_u32 s16, 29
	s_cbranch_scc0 .LBB0_979
	s_cmpk_lt_u32 s35, 0x100
	s_cbranch_scc0 .LBB0_982
	s_barrier

.LBB0_1059:
	ds_read_b128 v[128:131], v165
	ds_read_b128 v[132:135], v165 offset:1024
	ds_read_b128 v[136:139], v165 offset:2048
	ds_read_b128 v[140:143], v165 offset:3072
	ds_read_b128 v[156:159], v166
	ds_read_b128 v[168:171], v166 offset:1024
	ds_read_b128 v[172:175], v166 offset:2048
	ds_read_b128 v[176:179], v166 offset:3072
	s_add_u32 s38, s36, 0x100
	s_addc_u32 s39, s37, 0
	s_cmpk_eq_i32 s59, 0x54
	s_cselect_b32 s43, s5, s39
	s_cselect_b32 s42, s4, s38
	s_cselect_b32 s41, s27, s58
	s_cselect_b32 s40, s26, s57
	v_lshl_add_u64 v[160:161], s[36:37], 0, v[148:149]
	s_add_i32 m0, s9, 0xc000
	ds_read_b128 v[180:183], v167
	ds_read_b128 v[184:187], v167 offset:1024
	ds_read_b128 v[188:191], v167 offset:2048
	ds_read_b128 v[192:195], v167 offset:3072
	ds_read_b128 v[196:199], v167 offset:4096
	ds_read_b128 v[200:203], v167 offset:5120
	ds_read_b128 v[204:207], v167 offset:6144
	ds_read_b128 v[208:211], v167 offset:7168
	global_load_lds_dwordx4 v[160:161], off
	v_lshl_add_u64 v[160:161], s[36:37], 0, v[150:151]
	s_add_i32 m0, s9, 0xe000
	s_nop 0
	global_load_lds_dwordx4 v[160:161], off
	s_waitcnt vmcnt(8)
	s_waitcnt lgkmcnt(0)
	s_barrier
	s_waitcnt lgkmcnt(0)
	v_mfma_f32_16x16x32_bf16 v[124:127], v[128:131], v[180:183], v[124:127]
	v_mfma_f32_16x16x32_bf16 v[120:123], v[136:139], v[180:183], v[120:123]
	v_mfma_f32_16x16x32_bf16 v[116:119], v[128:131], v[188:191], v[116:119]
	v_mfma_f32_16x16x32_bf16 v[112:115], v[136:139], v[188:191], v[112:115]
	v_mfma_f32_16x16x32_bf16 v[108:111], v[128:131], v[196:199], v[108:111]
	v_mfma_f32_16x16x32_bf16 v[96:99], v[136:139], v[196:199], v[96:99]
	v_mfma_f32_16x16x32_bf16 v[80:83], v[128:131], v[204:207], v[80:83]
	v_mfma_f32_16x16x32_bf16 v[72:75], v[136:139], v[204:207], v[72:75]
	v_mfma_f32_16x16x32_bf16 v[124:127], v[132:135], v[184:187], v[124:127]
	v_mfma_f32_16x16x32_bf16 v[120:123], v[140:143], v[184:187], v[120:123]
	v_mfma_f32_16x16x32_bf16 v[116:119], v[132:135], v[192:195], v[116:119]
	v_mfma_f32_16x16x32_bf16 v[112:115], v[140:143], v[192:195], v[112:115]
	v_mfma_f32_16x16x32_bf16 v[108:111], v[132:135], v[200:203], v[108:111]
	v_mfma_f32_16x16x32_bf16 v[96:99], v[140:143], v[200:203], v[96:99]
	v_mfma_f32_16x16x32_bf16 v[80:83], v[132:135], v[208:211], v[80:83]
	v_mfma_f32_16x16x32_bf16 v[72:75], v[140:143], v[208:211], v[72:75]
	v_mfma_f32_16x16x32_bf16 v[104:107], v[156:159], v[180:183], v[104:107]
	v_mfma_f32_16x16x32_bf16 v[100:103], v[172:175], v[180:183], v[100:103]
	v_mfma_f32_16x16x32_bf16 v[92:95], v[156:159], v[188:191], v[92:95]
	v_mfma_f32_16x16x32_bf16 v[88:91], v[172:175], v[188:191], v[88:91]
	v_mfma_f32_16x16x32_bf16 v[84:87], v[156:159], v[196:199], v[84:87]
	v_mfma_f32_16x16x32_bf16 v[76:79], v[172:175], v[196:199], v[76:79]
	v_mfma_f32_16x16x32_bf16 v[68:71], v[156:159], v[204:207], v[68:71]
	v_mfma_f32_16x16x32_bf16 v[64:67], v[172:175], v[204:207], v[64:67]
	v_mfma_f32_16x16x32_bf16 v[104:107], v[168:171], v[184:187], v[104:107]
	v_mfma_f32_16x16x32_bf16 v[100:103], v[176:179], v[184:187], v[100:103]
	v_mfma_f32_16x16x32_bf16 v[92:95], v[168:171], v[192:195], v[92:95]
	v_mfma_f32_16x16x32_bf16 v[88:91], v[176:179], v[192:195], v[88:91]
	v_mfma_f32_16x16x32_bf16 v[84:87], v[168:171], v[200:203], v[84:87]
	v_mfma_f32_16x16x32_bf16 v[76:79], v[176:179], v[200:203], v[76:79]
	v_mfma_f32_16x16x32_bf16 v[68:71], v[168:171], v[208:211], v[68:71]
	v_mfma_f32_16x16x32_bf16 v[64:67], v[176:179], v[208:211], v[64:67]
	s_barrier
	s_add_i32 s36, s51, s8
	v_lshl_add_u64 v[160:161], s[40:41], 0, v[144:145]
	s_mov_b32 m0, s36
	ds_read_b128 v[180:183], v167 offset:16384
	ds_read_b128 v[184:187], v167 offset:17408
	ds_read_b128 v[188:191], v167 offset:18432
	ds_read_b128 v[192:195], v167 offset:19456
	ds_read_b128 v[196:199], v167 offset:20480
	ds_read_b128 v[200:203], v167 offset:21504
	ds_read_b128 v[204:207], v167 offset:22528
	ds_read_b128 v[208:211], v167 offset:23552
	global_load_lds_dwordx4 v[160:161], off
	s_add_i32 m0, s36, 0x2000
	s_add_u32 s36, s40, 0x160000
	v_lshl_add_u64 v[212:213], s[40:41], 0, v[146:147]
	s_addc_u32 s37, s41, 0
	s_add_i32 s60, s52, s8
	global_load_lds_dwordx4 v[212:213], off
	v_lshl_add_u64 v[214:215], s[36:37], 0, v[144:145]
	s_mov_b32 m0, s60
	v_lshl_add_u64 v[216:217], s[42:43], 0, v[146:147]
	global_load_lds_dwordx4 v[214:215], off
	v_lshl_add_u64 v[214:215], s[36:37], 0, v[146:147]
	s_add_i32 m0, s60, 0x2000
	s_nop 0
	global_load_lds_dwordx4 v[214:215], off
	v_lshl_add_u64 v[214:215], s[42:43], 0, v[144:145]
	s_mov_b32 m0, s9
	s_nop 0
	global_load_lds_dwordx4 v[214:215], off
	s_mov_b32 m0, s45
	s_nop 0
	global_load_lds_dwordx4 v[216:217], off
	s_waitcnt vmcnt(8)
	s_waitcnt lgkmcnt(0)
	s_barrier
	s_waitcnt lgkmcnt(0)
	v_mfma_f32_16x16x32_bf16 v[60:63], v[128:131], v[180:183], v[60:63]
	v_mfma_f32_16x16x32_bf16 v[56:59], v[136:139], v[180:183], v[56:59]
	v_mfma_f32_16x16x32_bf16 v[52:55], v[128:131], v[188:191], v[52:55]
	v_mfma_f32_16x16x32_bf16 v[48:51], v[136:139], v[188:191], v[48:51]
	v_mfma_f32_16x16x32_bf16 v[44:47], v[128:131], v[196:199], v[44:47]
	v_mfma_f32_16x16x32_bf16 v[32:35], v[136:139], v[196:199], v[32:35]
	v_mfma_f32_16x16x32_bf16 v[16:19], v[128:131], v[204:207], v[16:19]
	v_mfma_f32_16x16x32_bf16 v[8:11], v[136:139], v[204:207], v[8:11]
	v_mfma_f32_16x16x32_bf16 v[60:63], v[132:135], v[184:187], v[60:63]
	v_mfma_f32_16x16x32_bf16 v[56:59], v[140:143], v[184:187], v[56:59]
	v_mfma_f32_16x16x32_bf16 v[52:55], v[132:135], v[192:195], v[52:55]
	v_mfma_f32_16x16x32_bf16 v[48:51], v[140:143], v[192:195], v[48:51]
	v_mfma_f32_16x16x32_bf16 v[44:47], v[132:135], v[200:203], v[44:47]
	v_mfma_f32_16x16x32_bf16 v[32:35], v[140:143], v[200:203], v[32:35]
	v_mfma_f32_16x16x32_bf16 v[16:19], v[132:135], v[208:211], v[16:19]
	v_mfma_f32_16x16x32_bf16 v[8:11], v[140:143], v[208:211], v[8:11]
	v_mfma_f32_16x16x32_bf16 v[40:43], v[156:159], v[180:183], v[40:43]
	v_mfma_f32_16x16x32_bf16 v[36:39], v[172:175], v[180:183], v[36:39]
	v_mfma_f32_16x16x32_bf16 v[28:31], v[156:159], v[188:191], v[28:31]
	v_mfma_f32_16x16x32_bf16 v[24:27], v[172:175], v[188:191], v[24:27]
	v_mfma_f32_16x16x32_bf16 v[20:23], v[156:159], v[196:199], v[20:23]
	v_mfma_f32_16x16x32_bf16 v[12:15], v[172:175], v[196:199], v[12:15]
	v_mfma_f32_16x16x32_bf16 v[4:7], v[156:159], v[204:207], v[4:7]
	v_mfma_f32_16x16x32_bf16 v[0:3], v[172:175], v[204:207], v[0:3]
	v_mfma_f32_16x16x32_bf16 v[40:43], v[168:171], v[184:187], v[40:43]
	v_mfma_f32_16x16x32_bf16 v[36:39], v[176:179], v[184:187], v[36:39]
	v_mfma_f32_16x16x32_bf16 v[28:31], v[168:171], v[192:195], v[28:31]
	v_mfma_f32_16x16x32_bf16 v[24:27], v[176:179], v[192:195], v[24:27]
	v_mfma_f32_16x16x32_bf16 v[20:23], v[168:171], v[200:203], v[20:23]
	v_mfma_f32_16x16x32_bf16 v[12:15], v[176:179], v[200:203], v[12:15]
	v_mfma_f32_16x16x32_bf16 v[4:7], v[168:171], v[208:211], v[4:7]
	v_mfma_f32_16x16x32_bf16 v[0:3], v[176:179], v[208:211], v[0:3]
	s_barrier
	s_add_i32 s60, 0, 0x18000
	s_add_i32 s61, 0, 0x1c000
	v_add_u32_e32 v140, s60, v163
	v_add_u32_e32 v176, s61, v163
	ds_read_b128 v[128:131], v140
	ds_read_b128 v[132:135], v140 offset:1024
	ds_read_b128 v[136:139], v140 offset:2048
	ds_read_b128 v[140:143], v140 offset:3072
	ds_read_b128 v[156:159], v176
	ds_read_b128 v[168:171], v176 offset:1024
	ds_read_b128 v[172:175], v176 offset:2048
	ds_read_b128 v[176:179], v176 offset:3072
	s_add_u32 s36, s42, 0x160000
	s_addc_u32 s37, s43, 0
	s_mov_b32 m0, s46
	v_lshl_add_u64 v[218:219], s[36:37], 0, v[144:145]
	ds_read_b128 v[180:183], v167 offset:32768
	ds_read_b128 v[184:187], v167 offset:33792
	ds_read_b128 v[188:191], v167 offset:34816
	ds_read_b128 v[192:195], v167 offset:35840
	ds_read_b128 v[196:199], v167 offset:36864
	ds_read_b128 v[200:203], v167 offset:37888
	ds_read_b128 v[204:207], v167 offset:38912
	ds_read_b128 v[208:211], v167 offset:39936
	global_load_lds_dwordx4 v[218:219], off
	v_lshl_add_u64 v[218:219], s[36:37], 0, v[146:147]
	s_mov_b32 m0, s47
	s_nop 0
	global_load_lds_dwordx4 v[218:219], off
	s_waitcnt vmcnt(8)
	s_waitcnt lgkmcnt(0)
	s_barrier
	s_waitcnt lgkmcnt(0)
	v_mfma_f32_16x16x32_bf16 v[124:127], v[128:131], v[180:183], v[124:127]
	v_mfma_f32_16x16x32_bf16 v[120:123], v[136:139], v[180:183], v[120:123]
	v_mfma_f32_16x16x32_bf16 v[116:119], v[128:131], v[188:191], v[116:119]
	v_mfma_f32_16x16x32_bf16 v[112:115], v[136:139], v[188:191], v[112:115]
	v_mfma_f32_16x16x32_bf16 v[108:111], v[128:131], v[196:199], v[108:111]
	v_mfma_f32_16x16x32_bf16 v[96:99], v[136:139], v[196:199], v[96:99]
	v_mfma_f32_16x16x32_bf16 v[80:83], v[128:131], v[204:207], v[80:83]
	v_mfma_f32_16x16x32_bf16 v[72:75], v[136:139], v[204:207], v[72:75]
	v_mfma_f32_16x16x32_bf16 v[124:127], v[132:135], v[184:187], v[124:127]
	v_mfma_f32_16x16x32_bf16 v[120:123], v[140:143], v[184:187], v[120:123]
	v_mfma_f32_16x16x32_bf16 v[116:119], v[132:135], v[192:195], v[116:119]
	v_mfma_f32_16x16x32_bf16 v[112:115], v[140:143], v[192:195], v[112:115]
	v_mfma_f32_16x16x32_bf16 v[108:111], v[132:135], v[200:203], v[108:111]
	v_mfma_f32_16x16x32_bf16 v[96:99], v[140:143], v[200:203], v[96:99]
	v_mfma_f32_16x16x32_bf16 v[80:83], v[132:135], v[208:211], v[80:83]
	v_mfma_f32_16x16x32_bf16 v[72:75], v[140:143], v[208:211], v[72:75]
	v_mfma_f32_16x16x32_bf16 v[104:107], v[156:159], v[180:183], v[104:107]
	v_mfma_f32_16x16x32_bf16 v[100:103], v[172:175], v[180:183], v[100:103]
	v_mfma_f32_16x16x32_bf16 v[92:95], v[156:159], v[188:191], v[92:95]
	v_mfma_f32_16x16x32_bf16 v[88:91], v[172:175], v[188:191], v[88:91]
	v_mfma_f32_16x16x32_bf16 v[84:87], v[156:159], v[196:199], v[84:87]
	v_mfma_f32_16x16x32_bf16 v[76:79], v[172:175], v[196:199], v[76:79]
	v_mfma_f32_16x16x32_bf16 v[68:71], v[156:159], v[204:207], v[68:71]
	v_mfma_f32_16x16x32_bf16 v[64:67], v[172:175], v[204:207], v[64:67]
	v_mfma_f32_16x16x32_bf16 v[104:107], v[168:171], v[184:187], v[104:107]
	v_mfma_f32_16x16x32_bf16 v[100:103], v[176:179], v[184:187], v[100:103]
	v_mfma_f32_16x16x32_bf16 v[92:95], v[168:171], v[192:195], v[92:95]
	v_mfma_f32_16x16x32_bf16 v[88:91], v[176:179], v[192:195], v[88:91]
	v_mfma_f32_16x16x32_bf16 v[84:87], v[168:171], v[200:203], v[84:87]
	v_mfma_f32_16x16x32_bf16 v[76:79], v[176:179], v[200:203], v[76:79]
	v_mfma_f32_16x16x32_bf16 v[68:71], v[168:171], v[208:211], v[68:71]
	v_mfma_f32_16x16x32_bf16 v[64:67], v[176:179], v[208:211], v[64:67]
	s_barrier
	s_add_i32 s36, s60, s8
	v_lshl_add_u64 v[160:161], v[160:161], 0, s[16:17]
	s_mov_b32 m0, s36
	ds_read_b128 v[180:183], v167 offset:49152
	ds_read_b128 v[184:187], v167 offset:50176
	ds_read_b128 v[188:191], v167 offset:51200
	ds_read_b128 v[192:195], v167 offset:52224
	ds_read_b128 v[196:199], v167 offset:53248
	ds_read_b128 v[200:203], v167 offset:54272
	ds_read_b128 v[204:207], v167 offset:55296
	ds_read_b128 v[208:211], v167 offset:56320
	global_load_lds_dwordx4 v[160:161], off
	s_add_i32 m0, s36, 0x2000
	s_add_u32 s36, s40, 0x160080
	v_lshl_add_u64 v[160:161], v[212:213], 0, s[16:17]
	s_addc_u32 s37, s41, 0
	s_add_i32 s40, s61, s8
	global_load_lds_dwordx4 v[160:161], off
	v_lshl_add_u64 v[160:161], s[36:37], 0, v[144:145]
	s_mov_b32 m0, s40
	s_nop 0
	global_load_lds_dwordx4 v[160:161], off
	v_lshl_add_u64 v[160:161], s[36:37], 0, v[146:147]
	s_add_i32 m0, s40, 0x2000
	s_nop 0
	global_load_lds_dwordx4 v[160:161], off
	v_lshl_add_u64 v[160:161], v[214:215], 0, s[16:17]
	s_mov_b32 m0, s49
	s_nop 0
	global_load_lds_dwordx4 v[160:161], off
	v_lshl_add_u64 v[160:161], v[216:217], 0, s[16:17]
	s_mov_b32 m0, s50
	s_nop 0
	global_load_lds_dwordx4 v[160:161], off
	s_waitcnt vmcnt(8)
	s_waitcnt lgkmcnt(0)
	s_barrier
	s_waitcnt lgkmcnt(0)
	v_mfma_f32_16x16x32_bf16 v[60:63], v[128:131], v[180:183], v[60:63]
	v_mfma_f32_16x16x32_bf16 v[56:59], v[136:139], v[180:183], v[56:59]
	v_mfma_f32_16x16x32_bf16 v[52:55], v[128:131], v[188:191], v[52:55]
	v_mfma_f32_16x16x32_bf16 v[48:51], v[136:139], v[188:191], v[48:51]
	v_mfma_f32_16x16x32_bf16 v[44:47], v[128:131], v[196:199], v[44:47]
	v_mfma_f32_16x16x32_bf16 v[32:35], v[136:139], v[196:199], v[32:35]
	v_mfma_f32_16x16x32_bf16 v[16:19], v[128:131], v[204:207], v[16:19]
	v_mfma_f32_16x16x32_bf16 v[8:11], v[136:139], v[204:207], v[8:11]
	v_mfma_f32_16x16x32_bf16 v[60:63], v[132:135], v[184:187], v[60:63]
	v_mfma_f32_16x16x32_bf16 v[56:59], v[140:143], v[184:187], v[56:59]
	v_mfma_f32_16x16x32_bf16 v[52:55], v[132:135], v[192:195], v[52:55]
	v_mfma_f32_16x16x32_bf16 v[48:51], v[140:143], v[192:195], v[48:51]
	v_mfma_f32_16x16x32_bf16 v[44:47], v[132:135], v[200:203], v[44:47]
	v_mfma_f32_16x16x32_bf16 v[32:35], v[140:143], v[200:203], v[32:35]
	v_mfma_f32_16x16x32_bf16 v[16:19], v[132:135], v[208:211], v[16:19]
	v_mfma_f32_16x16x32_bf16 v[8:11], v[140:143], v[208:211], v[8:11]
	v_mfma_f32_16x16x32_bf16 v[40:43], v[156:159], v[180:183], v[40:43]
	v_mfma_f32_16x16x32_bf16 v[36:39], v[172:175], v[180:183], v[36:39]
	v_mfma_f32_16x16x32_bf16 v[28:31], v[156:159], v[188:191], v[28:31]
	v_mfma_f32_16x16x32_bf16 v[24:27], v[172:175], v[188:191], v[24:27]
	v_mfma_f32_16x16x32_bf16 v[20:23], v[156:159], v[196:199], v[20:23]
	v_mfma_f32_16x16x32_bf16 v[12:15], v[172:175], v[196:199], v[12:15]
	v_mfma_f32_16x16x32_bf16 v[4:7], v[156:159], v[204:207], v[4:7]
	v_mfma_f32_16x16x32_bf16 v[0:3], v[172:175], v[204:207], v[0:3]
	v_mfma_f32_16x16x32_bf16 v[40:43], v[168:171], v[184:187], v[40:43]
	v_mfma_f32_16x16x32_bf16 v[36:39], v[176:179], v[184:187], v[36:39]
	v_mfma_f32_16x16x32_bf16 v[28:31], v[168:171], v[192:195], v[28:31]
	v_mfma_f32_16x16x32_bf16 v[24:27], v[176:179], v[192:195], v[24:27]
	v_mfma_f32_16x16x32_bf16 v[20:23], v[168:171], v[200:203], v[20:23]
	v_mfma_f32_16x16x32_bf16 v[12:15], v[176:179], v[200:203], v[12:15]
	v_mfma_f32_16x16x32_bf16 v[4:7], v[168:171], v[208:211], v[4:7]
	v_mfma_f32_16x16x32_bf16 v[0:3], v[176:179], v[208:211], v[0:3]
	s_barrier
	s_add_i32 s59, s59, 2
	s_add_u32 s57, s57, 0x100
	s_addc_u32 s58, s58, 0
	s_cmpk_gt_u32 s59, 0x55
	s_mov_b64 s[36:37], s[38:39]
	s_cbranch_scc0 .LBB0_1059
	s_and_b64 vcc, exec, s[18:19]
	s_cbranch_vccz .LBB0_1062
	s_barrier

.LBB0_1089:
	ds_read_b128 v[128:131], v167
	ds_read_b128 v[132:135], v167 offset:1024
	ds_read_b128 v[136:139], v167 offset:2048
	ds_read_b128 v[140:143], v167 offset:3072
	ds_read_b128 v[156:159], v168
	ds_read_b128 v[160:163], v168 offset:1024
	ds_read_b128 v[170:173], v168 offset:2048
	ds_read_b128 v[174:177], v168 offset:3072
	s_add_u32 s22, s20, 0x100
	s_addc_u32 s23, s21, 0
	s_cmpk_eq_i32 s50, 0x54
	s_cselect_b32 s27, s5, s23
	s_cselect_b32 s26, s4, s22
	s_cselect_b32 s25, s19, s49
	s_cselect_b32 s24, s18, s48
	v_lshl_add_u64 v[210:211], s[20:21], 0, v[148:149]
	s_add_i32 m0, s34, 0xc000
	ds_read_b128 v[178:181], v169
	ds_read_b128 v[182:185], v169 offset:1024
	ds_read_b128 v[186:189], v169 offset:2048
	ds_read_b128 v[190:193], v169 offset:3072
	ds_read_b128 v[194:197], v169 offset:4096
	ds_read_b128 v[198:201], v169 offset:5120
	ds_read_b128 v[202:205], v169 offset:6144
	ds_read_b128 v[206:209], v169 offset:7168
	global_load_lds_dwordx4 v[210:211], off
	v_lshl_add_u64 v[210:211], s[20:21], 0, v[150:151]
	s_add_i32 m0, s34, 0xe000
	s_nop 0
	global_load_lds_dwordx4 v[210:211], off
	s_waitcnt vmcnt(8)
	s_waitcnt lgkmcnt(0)
	s_barrier
	s_waitcnt lgkmcnt(0)
	v_mfma_f32_16x16x32_bf16 v[124:127], v[128:131], v[178:181], v[124:127]
	v_mfma_f32_16x16x32_bf16 v[120:123], v[136:139], v[178:181], v[120:123]
	v_mfma_f32_16x16x32_bf16 v[116:119], v[128:131], v[186:189], v[116:119]
	v_mfma_f32_16x16x32_bf16 v[104:107], v[136:139], v[186:189], v[104:107]
	v_mfma_f32_16x16x32_bf16 v[96:99], v[128:131], v[194:197], v[96:99]
	v_mfma_f32_16x16x32_bf16 v[88:91], v[136:139], v[194:197], v[88:91]
	v_mfma_f32_16x16x32_bf16 v[80:83], v[128:131], v[202:205], v[80:83]
	v_mfma_f32_16x16x32_bf16 v[72:75], v[136:139], v[202:205], v[72:75]
	v_mfma_f32_16x16x32_bf16 v[124:127], v[132:135], v[182:185], v[124:127]
	v_mfma_f32_16x16x32_bf16 v[120:123], v[140:143], v[182:185], v[120:123]
	v_mfma_f32_16x16x32_bf16 v[116:119], v[132:135], v[190:193], v[116:119]
	v_mfma_f32_16x16x32_bf16 v[104:107], v[140:143], v[190:193], v[104:107]
	v_mfma_f32_16x16x32_bf16 v[96:99], v[132:135], v[198:201], v[96:99]
	v_mfma_f32_16x16x32_bf16 v[88:91], v[140:143], v[198:201], v[88:91]
	v_mfma_f32_16x16x32_bf16 v[80:83], v[132:135], v[206:209], v[80:83]
	v_mfma_f32_16x16x32_bf16 v[72:75], v[140:143], v[206:209], v[72:75]
	v_mfma_f32_16x16x32_bf16 v[112:115], v[156:159], v[178:181], v[112:115]
	v_mfma_f32_16x16x32_bf16 v[108:111], v[170:173], v[178:181], v[108:111]
	v_mfma_f32_16x16x32_bf16 v[100:103], v[156:159], v[186:189], v[100:103]
	v_mfma_f32_16x16x32_bf16 v[92:95], v[170:173], v[186:189], v[92:95]
	v_mfma_f32_16x16x32_bf16 v[84:87], v[156:159], v[194:197], v[84:87]
	v_mfma_f32_16x16x32_bf16 v[76:79], v[170:173], v[194:197], v[76:79]
	v_mfma_f32_16x16x32_bf16 v[68:71], v[156:159], v[202:205], v[68:71]
	v_mfma_f32_16x16x32_bf16 v[64:67], v[170:173], v[202:205], v[64:67]
	v_mfma_f32_16x16x32_bf16 v[112:115], v[160:163], v[182:185], v[112:115]
	v_mfma_f32_16x16x32_bf16 v[108:111], v[174:177], v[182:185], v[108:111]
	v_mfma_f32_16x16x32_bf16 v[100:103], v[160:163], v[190:193], v[100:103]
	v_mfma_f32_16x16x32_bf16 v[92:95], v[174:177], v[190:193], v[92:95]
	v_mfma_f32_16x16x32_bf16 v[84:87], v[160:163], v[198:201], v[84:87]
	v_mfma_f32_16x16x32_bf16 v[76:79], v[174:177], v[198:201], v[76:79]
	v_mfma_f32_16x16x32_bf16 v[68:71], v[160:163], v[206:209], v[68:71]
	v_mfma_f32_16x16x32_bf16 v[64:67], v[174:177], v[206:209], v[64:67]
	s_barrier
	s_add_i32 s20, s41, s33
	v_lshl_add_u64 v[210:211], s[24:25], 0, v[144:145]
	s_mov_b32 m0, s20
	ds_read_b128 v[178:181], v169 offset:16384
	ds_read_b128 v[182:185], v169 offset:17408
	ds_read_b128 v[186:189], v169 offset:18432
	ds_read_b128 v[190:193], v169 offset:19456
	ds_read_b128 v[194:197], v169 offset:20480
	ds_read_b128 v[198:201], v169 offset:21504
	ds_read_b128 v[202:205], v169 offset:22528
	ds_read_b128 v[206:209], v169 offset:23552
	global_load_lds_dwordx4 v[210:211], off
	s_add_i32 m0, s20, 0x2000
	s_add_u32 s20, s24, 0x160000
	v_lshl_add_u64 v[212:213], s[24:25], 0, v[146:147]
	s_addc_u32 s21, s25, 0
	s_add_i32 s51, s42, s33
	global_load_lds_dwordx4 v[212:213], off
	v_lshl_add_u64 v[214:215], s[20:21], 0, v[144:145]
	s_mov_b32 m0, s51
	v_lshl_add_u64 v[216:217], s[26:27], 0, v[146:147]
	global_load_lds_dwordx4 v[214:215], off
	v_lshl_add_u64 v[214:215], s[20:21], 0, v[146:147]
	s_add_i32 m0, s51, 0x2000
	s_nop 0
	global_load_lds_dwordx4 v[214:215], off
	v_lshl_add_u64 v[214:215], s[26:27], 0, v[144:145]
	s_mov_b32 m0, s34
	s_nop 0
	global_load_lds_dwordx4 v[214:215], off
	s_mov_b32 m0, s36
	s_nop 0
	global_load_lds_dwordx4 v[216:217], off
	s_waitcnt vmcnt(8)
	s_waitcnt lgkmcnt(0)
	s_barrier
	s_waitcnt lgkmcnt(0)
	v_mfma_f32_16x16x32_bf16 v[60:63], v[128:131], v[178:181], v[60:63]
	v_mfma_f32_16x16x32_bf16 v[56:59], v[136:139], v[178:181], v[56:59]
	v_mfma_f32_16x16x32_bf16 v[48:51], v[128:131], v[186:189], v[48:51]
	v_mfma_f32_16x16x32_bf16 v[40:43], v[136:139], v[186:189], v[40:43]
	v_mfma_f32_16x16x32_bf16 v[32:35], v[128:131], v[194:197], v[32:35]
	v_mfma_f32_16x16x32_bf16 v[24:27], v[136:139], v[194:197], v[24:27]
	v_mfma_f32_16x16x32_bf16 v[16:19], v[128:131], v[202:205], v[16:19]
	v_mfma_f32_16x16x32_bf16 v[8:11], v[136:139], v[202:205], v[8:11]
	v_mfma_f32_16x16x32_bf16 v[60:63], v[132:135], v[182:185], v[60:63]
	v_mfma_f32_16x16x32_bf16 v[56:59], v[140:143], v[182:185], v[56:59]
	v_mfma_f32_16x16x32_bf16 v[48:51], v[132:135], v[190:193], v[48:51]
	v_mfma_f32_16x16x32_bf16 v[40:43], v[140:143], v[190:193], v[40:43]
	v_mfma_f32_16x16x32_bf16 v[32:35], v[132:135], v[198:201], v[32:35]
	v_mfma_f32_16x16x32_bf16 v[24:27], v[140:143], v[198:201], v[24:27]
	v_mfma_f32_16x16x32_bf16 v[16:19], v[132:135], v[206:209], v[16:19]
	v_mfma_f32_16x16x32_bf16 v[8:11], v[140:143], v[206:209], v[8:11]
	v_mfma_f32_16x16x32_bf16 v[52:55], v[156:159], v[178:181], v[52:55]
	v_mfma_f32_16x16x32_bf16 v[44:47], v[170:173], v[178:181], v[44:47]
	v_mfma_f32_16x16x32_bf16 v[36:39], v[156:159], v[186:189], v[36:39]
	v_mfma_f32_16x16x32_bf16 v[28:31], v[170:173], v[186:189], v[28:31]
	v_mfma_f32_16x16x32_bf16 v[20:23], v[156:159], v[194:197], v[20:23]
	v_mfma_f32_16x16x32_bf16 v[12:15], v[170:173], v[194:197], v[12:15]
	v_mfma_f32_16x16x32_bf16 v[4:7], v[156:159], v[202:205], v[4:7]
	v_mfma_f32_16x16x32_bf16 v[0:3], v[170:173], v[202:205], v[0:3]
	v_mfma_f32_16x16x32_bf16 v[52:55], v[160:163], v[182:185], v[52:55]
	v_mfma_f32_16x16x32_bf16 v[44:47], v[174:177], v[182:185], v[44:47]
	v_mfma_f32_16x16x32_bf16 v[36:39], v[160:163], v[190:193], v[36:39]
	v_mfma_f32_16x16x32_bf16 v[28:31], v[174:177], v[190:193], v[28:31]
	v_mfma_f32_16x16x32_bf16 v[20:23], v[160:163], v[198:201], v[20:23]
	v_mfma_f32_16x16x32_bf16 v[12:15], v[174:177], v[198:201], v[12:15]
	v_mfma_f32_16x16x32_bf16 v[4:7], v[160:163], v[206:209], v[4:7]
	v_mfma_f32_16x16x32_bf16 v[0:3], v[174:177], v[206:209], v[0:3]
	s_barrier
	s_add_i32 s51, 0, 0x18000
	s_add_i32 s52, 0, 0x1c000
	v_add_u32_e32 v140, s51, v165
	v_add_u32_e32 v174, s52, v165
	ds_read_b128 v[128:131], v140
	ds_read_b128 v[132:135], v140 offset:1024
	ds_read_b128 v[136:139], v140 offset:2048
	ds_read_b128 v[140:143], v140 offset:3072
	ds_read_b128 v[156:159], v174
	ds_read_b128 v[160:163], v174 offset:1024
	ds_read_b128 v[170:173], v174 offset:2048
	ds_read_b128 v[174:177], v174 offset:3072
	s_add_u32 s20, s26, 0x160000
	s_addc_u32 s21, s27, 0
	s_mov_b32 m0, s37
	v_lshl_add_u64 v[218:219], s[20:21], 0, v[144:145]
	ds_read_b128 v[178:181], v169 offset:32768
	ds_read_b128 v[182:185], v169 offset:33792
	ds_read_b128 v[186:189], v169 offset:34816
	ds_read_b128 v[190:193], v169 offset:35840
	ds_read_b128 v[194:197], v169 offset:36864
	ds_read_b128 v[198:201], v169 offset:37888
	ds_read_b128 v[202:205], v169 offset:38912
	ds_read_b128 v[206:209], v169 offset:39936
	global_load_lds_dwordx4 v[218:219], off
	v_lshl_add_u64 v[218:219], s[20:21], 0, v[146:147]
	s_mov_b32 m0, s38
	s_nop 0
	global_load_lds_dwordx4 v[218:219], off
	s_waitcnt vmcnt(8)
	s_waitcnt lgkmcnt(0)
	s_barrier
	s_waitcnt lgkmcnt(0)
	v_mfma_f32_16x16x32_bf16 v[124:127], v[128:131], v[178:181], v[124:127]
	v_mfma_f32_16x16x32_bf16 v[120:123], v[136:139], v[178:181], v[120:123]
	v_mfma_f32_16x16x32_bf16 v[116:119], v[128:131], v[186:189], v[116:119]
	v_mfma_f32_16x16x32_bf16 v[104:107], v[136:139], v[186:189], v[104:107]
	v_mfma_f32_16x16x32_bf16 v[96:99], v[128:131], v[194:197], v[96:99]
	v_mfma_f32_16x16x32_bf16 v[88:91], v[136:139], v[194:197], v[88:91]
	v_mfma_f32_16x16x32_bf16 v[80:83], v[128:131], v[202:205], v[80:83]
	v_mfma_f32_16x16x32_bf16 v[72:75], v[136:139], v[202:205], v[72:75]
	v_mfma_f32_16x16x32_bf16 v[124:127], v[132:135], v[182:185], v[124:127]
	v_mfma_f32_16x16x32_bf16 v[120:123], v[140:143], v[182:185], v[120:123]
	v_mfma_f32_16x16x32_bf16 v[116:119], v[132:135], v[190:193], v[116:119]
	v_mfma_f32_16x16x32_bf16 v[104:107], v[140:143], v[190:193], v[104:107]
	v_mfma_f32_16x16x32_bf16 v[96:99], v[132:135], v[198:201], v[96:99]
	v_mfma_f32_16x16x32_bf16 v[88:91], v[140:143], v[198:201], v[88:91]
	v_mfma_f32_16x16x32_bf16 v[80:83], v[132:135], v[206:209], v[80:83]
	v_mfma_f32_16x16x32_bf16 v[72:75], v[140:143], v[206:209], v[72:75]
	v_mfma_f32_16x16x32_bf16 v[112:115], v[156:159], v[178:181], v[112:115]
	v_mfma_f32_16x16x32_bf16 v[108:111], v[170:173], v[178:181], v[108:111]
	v_mfma_f32_16x16x32_bf16 v[100:103], v[156:159], v[186:189], v[100:103]
	v_mfma_f32_16x16x32_bf16 v[92:95], v[170:173], v[186:189], v[92:95]
	v_mfma_f32_16x16x32_bf16 v[84:87], v[156:159], v[194:197], v[84:87]
	v_mfma_f32_16x16x32_bf16 v[76:79], v[170:173], v[194:197], v[76:79]
	v_mfma_f32_16x16x32_bf16 v[68:71], v[156:159], v[202:205], v[68:71]
	v_mfma_f32_16x16x32_bf16 v[64:67], v[170:173], v[202:205], v[64:67]
	v_mfma_f32_16x16x32_bf16 v[112:115], v[160:163], v[182:185], v[112:115]
	v_mfma_f32_16x16x32_bf16 v[108:111], v[174:177], v[182:185], v[108:111]
	v_mfma_f32_16x16x32_bf16 v[100:103], v[160:163], v[190:193], v[100:103]
	v_mfma_f32_16x16x32_bf16 v[92:95], v[174:177], v[190:193], v[92:95]
	v_mfma_f32_16x16x32_bf16 v[84:87], v[160:163], v[198:201], v[84:87]
	v_mfma_f32_16x16x32_bf16 v[76:79], v[174:177], v[198:201], v[76:79]
	v_mfma_f32_16x16x32_bf16 v[68:71], v[160:163], v[206:209], v[68:71]
	v_mfma_f32_16x16x32_bf16 v[64:67], v[174:177], v[206:209], v[64:67]
	s_barrier
	s_add_i32 s20, s51, s33
	v_lshl_add_u64 v[210:211], v[210:211], 0, s[14:15]
	s_mov_b32 m0, s20
	ds_read_b128 v[178:181], v169 offset:49152
	ds_read_b128 v[182:185], v169 offset:50176
	ds_read_b128 v[186:189], v169 offset:51200
	ds_read_b128 v[190:193], v169 offset:52224
	ds_read_b128 v[194:197], v169 offset:53248
	ds_read_b128 v[198:201], v169 offset:54272
	ds_read_b128 v[202:205], v169 offset:55296
	ds_read_b128 v[206:209], v169 offset:56320
	global_load_lds_dwordx4 v[210:211], off
	s_add_i32 m0, s20, 0x2000
	s_add_u32 s20, s24, 0x160080
	v_lshl_add_u64 v[210:211], v[212:213], 0, s[14:15]
	s_addc_u32 s21, s25, 0
	s_add_i32 s24, s52, s33
	global_load_lds_dwordx4 v[210:211], off
	v_lshl_add_u64 v[210:211], s[20:21], 0, v[144:145]
	s_mov_b32 m0, s24
	s_nop 0
	global_load_lds_dwordx4 v[210:211], off
	v_lshl_add_u64 v[210:211], s[20:21], 0, v[146:147]
	s_add_i32 m0, s24, 0x2000
	s_nop 0
	global_load_lds_dwordx4 v[210:211], off
	v_lshl_add_u64 v[210:211], v[214:215], 0, s[14:15]
	s_mov_b32 m0, s39
	s_nop 0
	global_load_lds_dwordx4 v[210:211], off
	v_lshl_add_u64 v[210:211], v[216:217], 0, s[14:15]
	s_mov_b32 m0, s40
	s_nop 0
	global_load_lds_dwordx4 v[210:211], off
	s_waitcnt vmcnt(8)
	s_waitcnt lgkmcnt(0)
	s_barrier
	s_waitcnt lgkmcnt(0)
	v_mfma_f32_16x16x32_bf16 v[60:63], v[128:131], v[178:181], v[60:63]
	v_mfma_f32_16x16x32_bf16 v[56:59], v[136:139], v[178:181], v[56:59]
	v_mfma_f32_16x16x32_bf16 v[48:51], v[128:131], v[186:189], v[48:51]
	v_mfma_f32_16x16x32_bf16 v[40:43], v[136:139], v[186:189], v[40:43]
	v_mfma_f32_16x16x32_bf16 v[32:35], v[128:131], v[194:197], v[32:35]
	v_mfma_f32_16x16x32_bf16 v[24:27], v[136:139], v[194:197], v[24:27]
	v_mfma_f32_16x16x32_bf16 v[16:19], v[128:131], v[202:205], v[16:19]
	v_mfma_f32_16x16x32_bf16 v[8:11], v[136:139], v[202:205], v[8:11]
	v_mfma_f32_16x16x32_bf16 v[60:63], v[132:135], v[182:185], v[60:63]
	v_mfma_f32_16x16x32_bf16 v[56:59], v[140:143], v[182:185], v[56:59]
	v_mfma_f32_16x16x32_bf16 v[48:51], v[132:135], v[190:193], v[48:51]
	v_mfma_f32_16x16x32_bf16 v[40:43], v[140:143], v[190:193], v[40:43]
	v_mfma_f32_16x16x32_bf16 v[32:35], v[132:135], v[198:201], v[32:35]
	v_mfma_f32_16x16x32_bf16 v[24:27], v[140:143], v[198:201], v[24:27]
	v_mfma_f32_16x16x32_bf16 v[16:19], v[132:135], v[206:209], v[16:19]
	v_mfma_f32_16x16x32_bf16 v[8:11], v[140:143], v[206:209], v[8:11]
	v_mfma_f32_16x16x32_bf16 v[52:55], v[156:159], v[178:181], v[52:55]
	v_mfma_f32_16x16x32_bf16 v[44:47], v[170:173], v[178:181], v[44:47]
	v_mfma_f32_16x16x32_bf16 v[36:39], v[156:159], v[186:189], v[36:39]
	v_mfma_f32_16x16x32_bf16 v[28:31], v[170:173], v[186:189], v[28:31]
	v_mfma_f32_16x16x32_bf16 v[20:23], v[156:159], v[194:197], v[20:23]
	v_mfma_f32_16x16x32_bf16 v[12:15], v[170:173], v[194:197], v[12:15]
	v_mfma_f32_16x16x32_bf16 v[4:7], v[156:159], v[202:205], v[4:7]
	v_mfma_f32_16x16x32_bf16 v[0:3], v[170:173], v[202:205], v[0:3]
	v_mfma_f32_16x16x32_bf16 v[52:55], v[160:163], v[182:185], v[52:55]
	v_mfma_f32_16x16x32_bf16 v[44:47], v[174:177], v[182:185], v[44:47]
	v_mfma_f32_16x16x32_bf16 v[36:39], v[160:163], v[190:193], v[36:39]
	v_mfma_f32_16x16x32_bf16 v[28:31], v[174:177], v[190:193], v[28:31]
	v_mfma_f32_16x16x32_bf16 v[20:23], v[160:163], v[198:201], v[20:23]
	v_mfma_f32_16x16x32_bf16 v[12:15], v[174:177], v[198:201], v[12:15]
	v_mfma_f32_16x16x32_bf16 v[4:7], v[160:163], v[206:209], v[4:7]
	v_mfma_f32_16x16x32_bf16 v[0:3], v[174:177], v[206:209], v[0:3]
	s_barrier
	s_add_i32 s50, s50, 2
	s_add_u32 s48, s48, 0x100
	s_addc_u32 s49, s49, 0
	s_cmpk_gt_u32 s50, 0x55
	s_mov_b64 s[20:21], s[22:23]
	s_cbranch_scc0 .LBB0_1089
	s_and_b64 vcc, exec, s[16:17]
	s_cbranch_vccz .LBB0_1092
	s_barrier
